# v39 + removed the s_setprio 0/1 flip between the two 16-MFMA groups of each super-phase (32 MFMAs issue uninterrupted; x3 phase probe -44us)
# baseline (speedup 1.0000x reference)
; #define PG8_STAGE(bufoff, gbase, voff) do { _Pragma("unroll") for (int _i = 0; _i < 2; ++_i) \
;         __builtin_amdgcn_global_load_lds((const unsigned*)((const char*)(gbase) + (voff)[_i]), (PG8_LAS unsigned*)(lds + (bufoff) + ldsw + _i * 8192), 16, 0, 0); } while (0)
; #define PG8_WAIT_V(n) asm volatile("s_waitcnt vmcnt(" #n ")" ::: "memory")
; #define PG8_WAIT_L(n) asm volatile("s_waitcnt lgkmcnt(" #n ")" ::: "memory")
; #define PG8_BAR __builtin_amdgcn_s_barrier()
; #define PG8_SCHED __builtin_amdgcn_sched_barrier(0)
;     ...
;             const char* a1 = cA + (size_t)(t + 1) * kstep;
;             const char* a2 = last ? nA : cA + (size_t)(t + 2) * kstep; const char* b2 = last ? nB : cB + (size_t)(t + 2) * kstep;
;             const char* a3 = a2 + kstep; const char* b3 = b2 + kstep;
;             if (last && has_next) S.a_ready(nxt);
;             if (last) E.pre(pre, cur, wr, fr);
;             if constexpr (MIDK > 0) { if (t == MIDK / BK) E.mid(acc, cur, wr, wc, fr, fq); }
;             if constexpr (SP2) {
;             PG8_LDB(B0, 0, 0); PG8_LDB(B1, 0, 1); PG8_SCHED; PG8_LDA(At, 0, 0); PG8_STAGE(PG8_SA(1, 1), a1 + hstep, voffA);
;             PG8_WAIT_V(8); PG8_WAIT_L(0); PG8_BAR; PG8_MMA(0, 0, At, B0); PG8_MMA(0, 1, At, B1); PG8_BAR; PG8_SCHED;
;             PG8_LDA(At, 0, 1); PG8_STAGE(PG8_SB(0, 0), b2, voffB); PG8_STAGE(PG8_SB(0, 1), b2 + hstep, voffB); PG8_STAGE(PG8_SA(0, 0), a2, voffA);
;             PG8_WAIT_V(8); PG8_WAIT_L(0); PG8_BAR; PG8_MMA(1, 0, At, B0); PG8_MMA(1, 1, At, B1); PG8_BAR; PG8_SCHED;
.LBB0_248:
	v_add_u32_e32 v155, s68, v149
	ds_read_b128 v[166:169], v155
	ds_read_b128 v[170:173], v155 offset:1024
	ds_read_b128 v[174:177], v155 offset:2048
	ds_read_b128 v[178:181], v155 offset:3072
	v_add_u32_e32 v155, s69, v149
	ds_read_b128 v[182:185], v155
	ds_read_b128 v[186:189], v155 offset:1024
	ds_read_b128 v[190:193], v155 offset:2048
	ds_read_b128 v[194:197], v155 offset:3072
	s_add_u32 s33, s50, 0xfffc0080
	s_addc_u32 s54, s51, -1
	s_and_b64 s[52:53], s[52:53], exec
	s_cselect_b32 s55, s25, s54
	s_cselect_b32 s54, s34, s33
	s_cselect_b32 s53, s21, s73
	s_cselect_b32 s52, s35, s72
	v_lshl_add_u64 v[210:211], s[50:51], 0, v[138:139]
	s_add_i32 m0, s59, 0xc000
	ds_read_b128 v[198:201], v153
	ds_read_b128 v[202:205], v153 offset:1024
	ds_read_b128 v[206:209], v153 offset:2048
	ds_read_b128 v[214:217], v153 offset:3072
	ds_read_b128 v[218:221], v153 offset:4096
	ds_read_b128 v[222:225], v153 offset:5120
	ds_read_b128 v[226:229], v153 offset:6144
	ds_read_b128 v[230:233], v153 offset:7168
	global_load_lds_dwordx4 v[210:211], off
	v_lshl_add_u64 v[210:211], s[50:51], 0, v[140:141]
	s_add_i32 m0, s59, 0xe000
	s_nop 0
	global_load_lds_dwordx4 v[210:211], off
	s_waitcnt vmcnt(8)
	s_waitcnt lgkmcnt(0)
	s_barrier
	s_setprio 1
	s_waitcnt lgkmcnt(0)
	v_mfma_i32_16x16x64_i8 v[124:127], v[166:169], v[198:201], v[124:127]
	v_mfma_i32_16x16x64_i8 v[124:127], v[170:173], v[202:205], v[124:127]
	v_mfma_i32_16x16x64_i8 v[116:119], v[174:177], v[198:201], v[116:119]
	v_mfma_i32_16x16x64_i8 v[116:119], v[178:181], v[202:205], v[116:119]
	v_mfma_i32_16x16x64_i8 v[108:111], v[166:169], v[206:209], v[108:111]
	v_mfma_i32_16x16x64_i8 v[108:111], v[170:173], v[214:217], v[108:111]
	v_mfma_i32_16x16x64_i8 v[100:103], v[174:177], v[206:209], v[100:103]
	v_mfma_i32_16x16x64_i8 v[100:103], v[178:181], v[214:217], v[100:103]
	v_mfma_i32_16x16x64_i8 v[92:95], v[166:169], v[218:221], v[92:95]
	v_mfma_i32_16x16x64_i8 v[92:95], v[170:173], v[222:225], v[92:95]
	v_mfma_i32_16x16x64_i8 v[84:87], v[174:177], v[218:221], v[84:87]
	v_mfma_i32_16x16x64_i8 v[84:87], v[178:181], v[222:225], v[84:87]
	v_mfma_i32_16x16x64_i8 v[76:79], v[166:169], v[226:229], v[76:79]
	v_mfma_i32_16x16x64_i8 v[76:79], v[170:173], v[230:233], v[76:79]
	v_mfma_i32_16x16x64_i8 v[68:71], v[174:177], v[226:229], v[68:71]
	v_mfma_i32_16x16x64_i8 v[68:71], v[178:181], v[230:233], v[68:71]
	v_mfma_i32_16x16x64_i8 v[120:123], v[182:185], v[198:201], v[120:123]
	v_mfma_i32_16x16x64_i8 v[120:123], v[186:189], v[202:205], v[120:123]
	v_mfma_i32_16x16x64_i8 v[112:115], v[190:193], v[198:201], v[112:115]
	v_mfma_i32_16x16x64_i8 v[112:115], v[194:197], v[202:205], v[112:115]
	v_mfma_i32_16x16x64_i8 v[104:107], v[182:185], v[206:209], v[104:107]
	v_mfma_i32_16x16x64_i8 v[104:107], v[186:189], v[214:217], v[104:107]
	v_mfma_i32_16x16x64_i8 v[96:99], v[190:193], v[206:209], v[96:99]
	v_mfma_i32_16x16x64_i8 v[96:99], v[194:197], v[214:217], v[96:99]
	v_mfma_i32_16x16x64_i8 v[88:91], v[182:185], v[218:221], v[88:91]
	v_mfma_i32_16x16x64_i8 v[88:91], v[186:189], v[222:225], v[88:91]
	v_mfma_i32_16x16x64_i8 v[80:83], v[190:193], v[218:221], v[80:83]
	v_mfma_i32_16x16x64_i8 v[80:83], v[194:197], v[222:225], v[80:83]
	v_mfma_i32_16x16x64_i8 v[72:75], v[182:185], v[226:229], v[72:75]
	v_mfma_i32_16x16x64_i8 v[72:75], v[186:189], v[230:233], v[72:75]
	v_mfma_i32_16x16x64_i8 v[64:67], v[190:193], v[226:229], v[64:67]
	v_mfma_i32_16x16x64_i8 v[64:67], v[194:197], v[230:233], v[64:67]
	s_setprio 0
	s_barrier
	s_add_i32 s33, s68, s56
	v_lshl_add_u64 v[210:211], s[52:53], 0, v[132:133]
	s_mov_b32 m0, s33
	ds_read_b128 v[198:201], v153 offset:16384
	ds_read_b128 v[202:205], v153 offset:17408
	ds_read_b128 v[206:209], v153 offset:18432
	ds_read_b128 v[214:217], v153 offset:19456
	ds_read_b128 v[218:221], v153 offset:20480
	ds_read_b128 v[222:225], v153 offset:21504
	ds_read_b128 v[226:229], v153 offset:22528
	ds_read_b128 v[230:233], v153 offset:23552
	global_load_lds_dwordx4 v[210:211], off
	s_add_i32 m0, s33, 0x2000
	s_add_u32 s76, s52, 0x40000
	v_lshl_add_u64 v[234:235], s[52:53], 0, v[128:129]
	s_addc_u32 s77, s53, 0
	s_add_i32 s33, s69, s56
	global_load_lds_dwordx4 v[234:235], off
	v_lshl_add_u64 v[236:237], s[76:77], 0, v[132:133]
	s_mov_b32 m0, s33
	v_lshl_add_u64 v[238:239], s[54:55], 0, v[130:131]
	global_load_lds_dwordx4 v[236:237], off
	v_lshl_add_u64 v[236:237], s[76:77], 0, v[128:129]
	s_add_i32 m0, s33, 0x2000
	s_nop 0
	global_load_lds_dwordx4 v[236:237], off
	v_lshl_add_u64 v[236:237], s[54:55], 0, v[134:135]
	s_mov_b32 m0, s59
	s_nop 0
	global_load_lds_dwordx4 v[236:237], off
	s_mov_b32 m0, s60
	s_nop 0
	global_load_lds_dwordx4 v[238:239], off
	s_waitcnt vmcnt(8)
	s_waitcnt lgkmcnt(0)
	s_barrier
; #define PG8_STAGE(bufoff, gbase, voff) do { _Pragma("unroll") for (int _i = 0; _i < 2; ++_i) \
;         __builtin_amdgcn_global_load_lds((const unsigned*)((const char*)(gbase) + (voff)[_i]), (PG8_LAS unsigned*)(lds + (bufoff) + ldsw + _i * 8192), 16, 0, 0); } while (0)
; #define PG8_WAIT_V(n) asm volatile("s_waitcnt vmcnt(" #n ")" ::: "memory")
; #define PG8_WAIT_L(n) asm volatile("s_waitcnt lgkmcnt(" #n ")" ::: "memory")
; #define PG8_BAR __builtin_amdgcn_s_barrier()
; #define PG8_SCHED __builtin_amdgcn_sched_barrier(0)
;     ...
;             PG8_WAIT_V(8); PG8_WAIT_L(0); PG8_BAR; PG8_MMA(1, 0, At, B0); PG8_MMA(1, 1, At, B1); PG8_BAR; PG8_SCHED;
;             PG8_LDB(B0, 1, 0); PG8_LDB(B1, 1, 1); PG8_SCHED; PG8_LDA(At, 1, 0); PG8_STAGE(PG8_SA(0, 1), a2 + hstep, voffA);
;             PG8_WAIT_V(8); PG8_WAIT_L(0); PG8_BAR; PG8_MMA(0, 0, At, B0); PG8_MMA(0, 1, At, B1); PG8_BAR; PG8_SCHED;
	s_setprio 1
	s_waitcnt lgkmcnt(0)
	v_mfma_i32_16x16x64_i8 v[60:63], v[166:169], v[198:201], v[60:63]
	v_mfma_i32_16x16x64_i8 v[60:63], v[170:173], v[202:205], v[60:63]
	v_mfma_i32_16x16x64_i8 v[52:55], v[174:177], v[198:201], v[52:55]
	v_mfma_i32_16x16x64_i8 v[52:55], v[178:181], v[202:205], v[52:55]
	v_mfma_i32_16x16x64_i8 v[44:47], v[166:169], v[206:209], v[44:47]
	v_mfma_i32_16x16x64_i8 v[44:47], v[170:173], v[214:217], v[44:47]
	v_mfma_i32_16x16x64_i8 v[36:39], v[174:177], v[206:209], v[36:39]
	v_mfma_i32_16x16x64_i8 v[36:39], v[178:181], v[214:217], v[36:39]
	v_mfma_i32_16x16x64_i8 v[28:31], v[166:169], v[218:221], v[28:31]
	v_mfma_i32_16x16x64_i8 v[28:31], v[170:173], v[222:225], v[28:31]
	v_mfma_i32_16x16x64_i8 v[20:23], v[174:177], v[218:221], v[20:23]
	v_mfma_i32_16x16x64_i8 v[20:23], v[178:181], v[222:225], v[20:23]
	v_mfma_i32_16x16x64_i8 v[12:15], v[166:169], v[226:229], v[12:15]
	v_mfma_i32_16x16x64_i8 v[12:15], v[170:173], v[230:233], v[12:15]
	v_mfma_i32_16x16x64_i8 v[4:7], v[174:177], v[226:229], v[4:7]
	v_mfma_i32_16x16x64_i8 v[4:7], v[178:181], v[230:233], v[4:7]
	v_mfma_i32_16x16x64_i8 v[56:59], v[182:185], v[198:201], v[56:59]
	v_mfma_i32_16x16x64_i8 v[56:59], v[186:189], v[202:205], v[56:59]
	v_mfma_i32_16x16x64_i8 v[48:51], v[190:193], v[198:201], v[48:51]
	v_mfma_i32_16x16x64_i8 v[48:51], v[194:197], v[202:205], v[48:51]
	v_mfma_i32_16x16x64_i8 v[40:43], v[182:185], v[206:209], v[40:43]
	v_mfma_i32_16x16x64_i8 v[40:43], v[186:189], v[214:217], v[40:43]
	v_mfma_i32_16x16x64_i8 v[32:35], v[190:193], v[206:209], v[32:35]
	v_mfma_i32_16x16x64_i8 v[32:35], v[194:197], v[214:217], v[32:35]
	v_mfma_i32_16x16x64_i8 v[24:27], v[182:185], v[218:221], v[24:27]
	v_mfma_i32_16x16x64_i8 v[24:27], v[186:189], v[222:225], v[24:27]
	v_mfma_i32_16x16x64_i8 v[16:19], v[190:193], v[218:221], v[16:19]
	v_mfma_i32_16x16x64_i8 v[16:19], v[194:197], v[222:225], v[16:19]
	v_mfma_i32_16x16x64_i8 v[8:11], v[182:185], v[226:229], v[8:11]
	v_mfma_i32_16x16x64_i8 v[8:11], v[186:189], v[230:233], v[8:11]
	v_mfma_i32_16x16x64_i8 v[0:3], v[190:193], v[226:229], v[0:3]
	v_mfma_i32_16x16x64_i8 v[0:3], v[194:197], v[230:233], v[0:3]
	s_setprio 0
	s_barrier
	s_add_i32 s33, 0, 0x18000
	v_add_u32_e32 v155, s33, v149
	s_add_i32 s75, 0, 0x1c000
	ds_read_b128 v[166:169], v155
	ds_read_b128 v[170:173], v155 offset:1024
	ds_read_b128 v[174:177], v155 offset:2048
	ds_read_b128 v[178:181], v155 offset:3072
	v_add_u32_e32 v155, s75, v149
	ds_read_b128 v[182:185], v155
	ds_read_b128 v[186:189], v155 offset:1024
	ds_read_b128 v[190:193], v155 offset:2048
	ds_read_b128 v[194:197], v155 offset:3072
	s_add_u32 s54, s54, 0x40000
	s_addc_u32 s55, s55, 0
	s_mov_b32 m0, s61
	v_lshl_add_u64 v[240:241], s[54:55], 0, v[134:135]
	ds_read_b128 v[198:201], v153 offset:32768
	ds_read_b128 v[202:205], v153 offset:33792
	ds_read_b128 v[206:209], v153 offset:34816
	ds_read_b128 v[214:217], v153 offset:35840
	ds_read_b128 v[218:221], v153 offset:36864
	ds_read_b128 v[222:225], v153 offset:37888
	ds_read_b128 v[226:229], v153 offset:38912
	ds_read_b128 v[230:233], v153 offset:39936
	global_load_lds_dwordx4 v[240:241], off
	v_lshl_add_u64 v[240:241], s[54:55], 0, v[130:131]
	s_mov_b32 m0, s62
	s_nop 0
	global_load_lds_dwordx4 v[240:241], off
	s_waitcnt vmcnt(8)
	s_waitcnt lgkmcnt(0)
	s_barrier
	s_setprio 1
	s_waitcnt lgkmcnt(0)
	v_mfma_i32_16x16x64_i8 v[124:127], v[166:169], v[198:201], v[124:127]
	v_mfma_i32_16x16x64_i8 v[124:127], v[170:173], v[202:205], v[124:127]
	v_mfma_i32_16x16x64_i8 v[116:119], v[174:177], v[198:201], v[116:119]
	v_mfma_i32_16x16x64_i8 v[116:119], v[178:181], v[202:205], v[116:119]
	v_mfma_i32_16x16x64_i8 v[108:111], v[166:169], v[206:209], v[108:111]
	v_mfma_i32_16x16x64_i8 v[108:111], v[170:173], v[214:217], v[108:111]
	v_mfma_i32_16x16x64_i8 v[100:103], v[174:177], v[206:209], v[100:103]
	v_mfma_i32_16x16x64_i8 v[100:103], v[178:181], v[214:217], v[100:103]
	v_mfma_i32_16x16x64_i8 v[92:95], v[166:169], v[218:221], v[92:95]
	v_mfma_i32_16x16x64_i8 v[92:95], v[170:173], v[222:225], v[92:95]
	v_mfma_i32_16x16x64_i8 v[84:87], v[174:177], v[218:221], v[84:87]
	v_mfma_i32_16x16x64_i8 v[84:87], v[178:181], v[222:225], v[84:87]
	v_mfma_i32_16x16x64_i8 v[76:79], v[166:169], v[226:229], v[76:79]
	v_mfma_i32_16x16x64_i8 v[76:79], v[170:173], v[230:233], v[76:79]
	v_mfma_i32_16x16x64_i8 v[68:71], v[174:177], v[226:229], v[68:71]
	v_mfma_i32_16x16x64_i8 v[68:71], v[178:181], v[230:233], v[68:71]
	v_mfma_i32_16x16x64_i8 v[120:123], v[182:185], v[198:201], v[120:123]
	v_mfma_i32_16x16x64_i8 v[120:123], v[186:189], v[202:205], v[120:123]
	v_mfma_i32_16x16x64_i8 v[112:115], v[190:193], v[198:201], v[112:115]
	v_mfma_i32_16x16x64_i8 v[112:115], v[194:197], v[202:205], v[112:115]
	v_mfma_i32_16x16x64_i8 v[104:107], v[182:185], v[206:209], v[104:107]
	v_mfma_i32_16x16x64_i8 v[104:107], v[186:189], v[214:217], v[104:107]
	v_mfma_i32_16x16x64_i8 v[96:99], v[190:193], v[206:209], v[96:99]
	v_mfma_i32_16x16x64_i8 v[96:99], v[194:197], v[214:217], v[96:99]
	v_mfma_i32_16x16x64_i8 v[88:91], v[182:185], v[218:221], v[88:91]
	v_mfma_i32_16x16x64_i8 v[88:91], v[186:189], v[222:225], v[88:91]
	v_mfma_i32_16x16x64_i8 v[80:83], v[190:193], v[218:221], v[80:83]
	v_mfma_i32_16x16x64_i8 v[80:83], v[194:197], v[222:225], v[80:83]
	v_mfma_i32_16x16x64_i8 v[72:75], v[182:185], v[226:229], v[72:75]
	v_mfma_i32_16x16x64_i8 v[72:75], v[186:189], v[230:233], v[72:75]
	v_mfma_i32_16x16x64_i8 v[64:67], v[190:193], v[226:229], v[64:67]
	v_mfma_i32_16x16x64_i8 v[64:67], v[194:197], v[230:233], v[64:67]
	s_setprio 0
	s_barrier
; #define PG8_STAGE(bufoff, gbase, voff) do { _Pragma("unroll") for (int _i = 0; _i < 2; ++_i) \
;         __builtin_amdgcn_global_load_lds((const unsigned*)((const char*)(gbase) + (voff)[_i]), (PG8_LAS unsigned*)(lds + (bufoff) + ldsw + _i * 8192), 16, 0, 0); } while (0)
; #define PG8_WAIT_V(n) asm volatile("s_waitcnt vmcnt(" #n ")" ::: "memory")
; #define PG8_WAIT_L(n) asm volatile("s_waitcnt lgkmcnt(" #n ")" ::: "memory")
; #define PG8_BAR __builtin_amdgcn_s_barrier()
; #define PG8_SCHED __builtin_amdgcn_sched_barrier(0)
;     ...
;             PG8_LDA(At, 1, 1); PG8_STAGE(PG8_SB(1, 0), b3, voffB); PG8_STAGE(PG8_SB(1, 1), b3 + hstep, voffB); PG8_STAGE(PG8_SA(1, 0), a3, voffA);
;             PG8_WAIT_V(8); PG8_WAIT_L(0); PG8_BAR; PG8_MMA(1, 0, At, B0); PG8_MMA(1, 1, At, B1); PG8_BAR; PG8_SCHED;
	s_add_i32 s33, s33, s56
	v_lshl_add_u64 v[210:211], v[210:211], 0, s[10:11]
	s_mov_b32 m0, s33
	ds_read_b128 v[198:201], v153 offset:49152
	ds_read_b128 v[202:205], v153 offset:50176
	ds_read_b128 v[206:209], v153 offset:51200
	ds_read_b128 v[214:217], v153 offset:52224
	ds_read_b128 v[218:221], v153 offset:53248
	ds_read_b128 v[222:225], v153 offset:54272
	ds_read_b128 v[226:229], v153 offset:55296
	ds_read_b128 v[230:233], v153 offset:56320
	global_load_lds_dwordx4 v[210:211], off
	s_add_i32 m0, s33, 0x2000
	s_add_u32 s52, s52, 0x40080
	v_lshl_add_u64 v[210:211], v[234:235], 0, s[10:11]
	s_addc_u32 s53, s53, 0
	s_add_i32 s33, s75, s56
	global_load_lds_dwordx4 v[210:211], off
	v_lshl_add_u64 v[210:211], s[52:53], 0, v[132:133]
	s_mov_b32 m0, s33
	s_nop 0
	global_load_lds_dwordx4 v[210:211], off
	v_lshl_add_u64 v[210:211], s[52:53], 0, v[128:129]
	s_add_i32 m0, s33, 0x2000
	s_nop 0
	global_load_lds_dwordx4 v[210:211], off
	v_lshl_add_u64 v[210:211], v[236:237], 0, s[10:11]
	s_mov_b32 m0, s64
	s_nop 0
	global_load_lds_dwordx4 v[210:211], off
	v_lshl_add_u64 v[210:211], v[238:239], 0, s[10:11]
	s_mov_b32 m0, s65
	s_nop 0
	global_load_lds_dwordx4 v[210:211], off
	s_waitcnt vmcnt(8)
	s_waitcnt lgkmcnt(0)
	s_barrier
	s_setprio 1
	s_waitcnt lgkmcnt(0)
	v_mfma_i32_16x16x64_i8 v[60:63], v[166:169], v[198:201], v[60:63]
	v_mfma_i32_16x16x64_i8 v[60:63], v[170:173], v[202:205], v[60:63]
	v_mfma_i32_16x16x64_i8 v[52:55], v[174:177], v[198:201], v[52:55]
	v_mfma_i32_16x16x64_i8 v[52:55], v[178:181], v[202:205], v[52:55]
	v_mfma_i32_16x16x64_i8 v[44:47], v[166:169], v[206:209], v[44:47]
	v_mfma_i32_16x16x64_i8 v[44:47], v[170:173], v[214:217], v[44:47]
	v_mfma_i32_16x16x64_i8 v[36:39], v[174:177], v[206:209], v[36:39]
	v_mfma_i32_16x16x64_i8 v[36:39], v[178:181], v[214:217], v[36:39]
	v_mfma_i32_16x16x64_i8 v[28:31], v[166:169], v[218:221], v[28:31]
	v_mfma_i32_16x16x64_i8 v[28:31], v[170:173], v[222:225], v[28:31]
	v_mfma_i32_16x16x64_i8 v[20:23], v[174:177], v[218:221], v[20:23]
	v_mfma_i32_16x16x64_i8 v[20:23], v[178:181], v[222:225], v[20:23]
	v_mfma_i32_16x16x64_i8 v[12:15], v[166:169], v[226:229], v[12:15]
	v_mfma_i32_16x16x64_i8 v[12:15], v[170:173], v[230:233], v[12:15]
	v_mfma_i32_16x16x64_i8 v[4:7], v[174:177], v[226:229], v[4:7]
	v_mfma_i32_16x16x64_i8 v[4:7], v[178:181], v[230:233], v[4:7]
	v_mfma_i32_16x16x64_i8 v[56:59], v[182:185], v[198:201], v[56:59]
	v_mfma_i32_16x16x64_i8 v[56:59], v[186:189], v[202:205], v[56:59]
	v_mfma_i32_16x16x64_i8 v[48:51], v[190:193], v[198:201], v[48:51]
	v_mfma_i32_16x16x64_i8 v[48:51], v[194:197], v[202:205], v[48:51]
	v_mfma_i32_16x16x64_i8 v[40:43], v[182:185], v[206:209], v[40:43]
	v_mfma_i32_16x16x64_i8 v[40:43], v[186:189], v[214:217], v[40:43]
	v_mfma_i32_16x16x64_i8 v[32:35], v[190:193], v[206:209], v[32:35]
	v_mfma_i32_16x16x64_i8 v[32:35], v[194:197], v[214:217], v[32:35]
	v_mfma_i32_16x16x64_i8 v[24:27], v[182:185], v[218:221], v[24:27]
	v_mfma_i32_16x16x64_i8 v[24:27], v[186:189], v[222:225], v[24:27]
	v_mfma_i32_16x16x64_i8 v[16:19], v[190:193], v[218:221], v[16:19]
	v_mfma_i32_16x16x64_i8 v[16:19], v[194:197], v[222:225], v[16:19]
	v_mfma_i32_16x16x64_i8 v[8:11], v[182:185], v[226:229], v[8:11]
	v_mfma_i32_16x16x64_i8 v[8:11], v[186:189], v[230:233], v[8:11]
	v_mfma_i32_16x16x64_i8 v[0:3], v[190:193], v[226:229], v[0:3]
	v_mfma_i32_16x16x64_i8 v[0:3], v[194:197], v[230:233], v[0:3]
	s_setprio 0
	s_barrier
	s_add_i32 s74, s74, 2
	s_add_u32 s50, s50, 0x100
	s_addc_u32 s51, s51, 0
	s_add_u32 s72, s72, 0x100
	s_addc_u32 s73, s73, 0
	s_cmp_gt_u32 s74, 13
	s_cbranch_scc1 .LBB0_251

; #define PG8_STAGE(bufoff, gbase, voff) do { _Pragma("unroll") for (int _i = 0; _i < 2; ++_i) \
;         __builtin_amdgcn_global_load_lds((const unsigned*)((const char*)(gbase) + (voff)[_i]), (PG8_LAS unsigned*)(lds + (bufoff) + ldsw + _i * 8192), 16, 0, 0); } while (0)
; #define PG8_WAIT_V(n) asm volatile("s_waitcnt vmcnt(" #n ")" ::: "memory")
; #define PG8_WAIT_L(n) asm volatile("s_waitcnt lgkmcnt(" #n ")" ::: "memory")
; #define PG8_BAR __builtin_amdgcn_s_barrier()
; #define PG8_SCHED __builtin_amdgcn_sched_barrier(0)
;     ...
;             const char* a1 = cA + (size_t)(t + 1) * kstep;
;             const char* a2 = last ? nA : cA + (size_t)(t + 2) * kstep; const char* b2 = last ? nB : cB + (size_t)(t + 2) * kstep;
;             const char* a3 = a2 + kstep; const char* b3 = b2 + kstep;
;             if (last && has_next) S.a_ready(nxt);
;             if (last) E.pre(pre, cur, wr, fr);
;             if constexpr (MIDK > 0) { if (t == MIDK / BK) E.mid(acc, cur, wr, wc, fr, fq); }
;             if constexpr (SP2) {
;             PG8_LDB(B0, 0, 0); PG8_LDB(B1, 0, 1); PG8_SCHED; PG8_LDA(At, 0, 0); PG8_STAGE(PG8_SA(1, 1), a1 + hstep, voffA);
;             PG8_WAIT_V(8); PG8_WAIT_L(0); PG8_BAR; PG8_MMA(0, 0, At, B0); PG8_MMA(0, 1, At, B1); PG8_BAR; PG8_SCHED;
;             PG8_LDA(At, 0, 1); PG8_STAGE(PG8_SB(0, 0), b2, voffB); PG8_STAGE(PG8_SB(0, 1), b2 + hstep, voffB); PG8_STAGE(PG8_SA(0, 0), a2, voffA);
;             PG8_WAIT_V(8); PG8_WAIT_L(0); PG8_BAR; PG8_MMA(1, 0, At, B0); PG8_MMA(1, 1, At, B1); PG8_BAR; PG8_SCHED;
.LBB0_335:
	ds_read_b128 v[128:131], v191
	ds_read_b128 v[132:135], v191 offset:1024
	ds_read_b128 v[136:139], v191 offset:2048
	ds_read_b128 v[140:143], v191 offset:3072
	ds_read_b128 v[144:147], v192
	ds_read_b128 v[148:151], v192 offset:1024
	ds_read_b128 v[168:171], v192 offset:2048
	ds_read_b128 v[172:175], v192 offset:3072
	s_add_u32 s33, s50, 0xffea0080
	s_addc_u32 s52, s51, -1
	s_cmpk_eq_i32 s72, 0x54
	s_cselect_b32 s55, s1, s52
	s_cselect_b32 s54, s0, s33
	s_cselect_b32 s53, s49, s35
	s_cselect_b32 s52, s48, s34
	v_lshl_add_u64 v[218:219], s[50:51], 0, v[160:161]
	s_add_i32 m0, s56, 0xc000
	ds_read_b128 v[176:179], v193
	ds_read_b128 v[180:183], v193 offset:1024
	ds_read_b128 v[184:187], v193 offset:2048
	ds_read_b128 v[196:199], v193 offset:3072
	ds_read_b128 v[200:203], v193 offset:4096
	ds_read_b128 v[204:207], v193 offset:5120
	ds_read_b128 v[208:211], v193 offset:6144
	ds_read_b128 v[214:217], v193 offset:7168
	global_load_lds_dwordx4 v[218:219], off
	v_lshl_add_u64 v[218:219], s[50:51], 0, v[162:163]
	s_add_i32 m0, s56, 0xe000
	s_nop 0
	global_load_lds_dwordx4 v[218:219], off
	s_waitcnt vmcnt(8)
	s_waitcnt lgkmcnt(0)
	s_barrier
	s_setprio 1
	s_waitcnt lgkmcnt(0)
	v_mfma_f32_16x16x32_bf16 v[124:127], v[128:131], v[176:179], v[124:127]
	v_mfma_f32_16x16x32_bf16 v[124:127], v[132:135], v[180:183], v[124:127]
	v_mfma_f32_16x16x32_bf16 v[120:123], v[136:139], v[176:179], v[120:123]
	v_mfma_f32_16x16x32_bf16 v[120:123], v[140:143], v[180:183], v[120:123]
	v_mfma_f32_16x16x32_bf16 v[108:111], v[128:131], v[184:187], v[108:111]
	v_mfma_f32_16x16x32_bf16 v[108:111], v[132:135], v[196:199], v[108:111]
	v_mfma_f32_16x16x32_bf16 v[104:107], v[136:139], v[184:187], v[104:107]
	v_mfma_f32_16x16x32_bf16 v[104:107], v[140:143], v[196:199], v[104:107]
	v_mfma_f32_16x16x32_bf16 v[92:95], v[128:131], v[200:203], v[92:95]
	v_mfma_f32_16x16x32_bf16 v[92:95], v[132:135], v[204:207], v[92:95]
	v_mfma_f32_16x16x32_bf16 v[88:91], v[136:139], v[200:203], v[88:91]
	v_mfma_f32_16x16x32_bf16 v[88:91], v[140:143], v[204:207], v[88:91]
	v_mfma_f32_16x16x32_bf16 v[76:79], v[128:131], v[208:211], v[76:79]
	v_mfma_f32_16x16x32_bf16 v[76:79], v[132:135], v[214:217], v[76:79]
	v_mfma_f32_16x16x32_bf16 v[72:75], v[136:139], v[208:211], v[72:75]
	v_mfma_f32_16x16x32_bf16 v[72:75], v[140:143], v[214:217], v[72:75]
	v_mfma_f32_16x16x32_bf16 v[116:119], v[144:147], v[176:179], v[116:119]
	v_mfma_f32_16x16x32_bf16 v[116:119], v[148:151], v[180:183], v[116:119]
	v_mfma_f32_16x16x32_bf16 v[112:115], v[168:171], v[176:179], v[112:115]
	v_mfma_f32_16x16x32_bf16 v[112:115], v[172:175], v[180:183], v[112:115]
	v_mfma_f32_16x16x32_bf16 v[100:103], v[144:147], v[184:187], v[100:103]
	v_mfma_f32_16x16x32_bf16 v[100:103], v[148:151], v[196:199], v[100:103]
	v_mfma_f32_16x16x32_bf16 v[96:99], v[168:171], v[184:187], v[96:99]
	v_mfma_f32_16x16x32_bf16 v[96:99], v[172:175], v[196:199], v[96:99]
	v_mfma_f32_16x16x32_bf16 v[84:87], v[144:147], v[200:203], v[84:87]
	v_mfma_f32_16x16x32_bf16 v[84:87], v[148:151], v[204:207], v[84:87]
	v_mfma_f32_16x16x32_bf16 v[80:83], v[168:171], v[200:203], v[80:83]
	v_mfma_f32_16x16x32_bf16 v[80:83], v[172:175], v[204:207], v[80:83]
	v_mfma_f32_16x16x32_bf16 v[68:71], v[144:147], v[208:211], v[68:71]
	v_mfma_f32_16x16x32_bf16 v[68:71], v[148:151], v[214:217], v[68:71]
	v_mfma_f32_16x16x32_bf16 v[64:67], v[168:171], v[208:211], v[64:67]
	v_mfma_f32_16x16x32_bf16 v[64:67], v[172:175], v[214:217], v[64:67]
	s_setprio 0
	s_barrier
	s_add_i32 s33, s66, s19
	v_lshl_add_u64 v[218:219], s[52:53], 0, v[154:155]
	s_mov_b32 m0, s33
	ds_read_b128 v[176:179], v193 offset:16384
	ds_read_b128 v[180:183], v193 offset:17408
	ds_read_b128 v[184:187], v193 offset:18432
	ds_read_b128 v[196:199], v193 offset:19456
	ds_read_b128 v[200:203], v193 offset:20480
	ds_read_b128 v[204:207], v193 offset:21504
	ds_read_b128 v[208:211], v193 offset:22528
	ds_read_b128 v[214:217], v193 offset:23552
	global_load_lds_dwordx4 v[218:219], off
	s_add_i32 m0, s33, 0x2000
	s_add_u32 s74, s52, 0x160000
	v_lshl_add_u64 v[220:221], s[52:53], 0, v[158:159]
	s_addc_u32 s75, s53, 0
	s_add_i32 s33, s67, s19
	global_load_lds_dwordx4 v[220:221], off
	v_lshl_add_u64 v[222:223], s[74:75], 0, v[154:155]
	s_mov_b32 m0, s33
	v_lshl_add_u64 v[224:225], s[54:55], 0, v[156:157]
	global_load_lds_dwordx4 v[222:223], off
	v_lshl_add_u64 v[222:223], s[74:75], 0, v[158:159]
	s_add_i32 m0, s33, 0x2000
	s_nop 0
	global_load_lds_dwordx4 v[222:223], off
	v_lshl_add_u64 v[222:223], s[54:55], 0, v[152:153]
	s_mov_b32 m0, s56
	s_nop 0
	global_load_lds_dwordx4 v[222:223], off
	s_mov_b32 m0, s57
	s_nop 0
	global_load_lds_dwordx4 v[224:225], off
	s_waitcnt vmcnt(8)
	s_waitcnt lgkmcnt(0)
	s_barrier
; #define PG8_STAGE(bufoff, gbase, voff) do { _Pragma("unroll") for (int _i = 0; _i < 2; ++_i) \
;         __builtin_amdgcn_global_load_lds((const unsigned*)((const char*)(gbase) + (voff)[_i]), (PG8_LAS unsigned*)(lds + (bufoff) + ldsw + _i * 8192), 16, 0, 0); } while (0)
; #define PG8_WAIT_V(n) asm volatile("s_waitcnt vmcnt(" #n ")" ::: "memory")
; #define PG8_WAIT_L(n) asm volatile("s_waitcnt lgkmcnt(" #n ")" ::: "memory")
; #define PG8_BAR __builtin_amdgcn_s_barrier()
; #define PG8_SCHED __builtin_amdgcn_sched_barrier(0)
;     ...
;             PG8_WAIT_V(8); PG8_WAIT_L(0); PG8_BAR; PG8_MMA(1, 0, At, B0); PG8_MMA(1, 1, At, B1); PG8_BAR; PG8_SCHED;
;             PG8_LDB(B0, 1, 0); PG8_LDB(B1, 1, 1); PG8_SCHED; PG8_LDA(At, 1, 0); PG8_STAGE(PG8_SA(0, 1), a2 + hstep, voffA);
;             PG8_WAIT_V(8); PG8_WAIT_L(0); PG8_BAR; PG8_MMA(0, 0, At, B0); PG8_MMA(0, 1, At, B1); PG8_BAR; PG8_SCHED;
	s_setprio 1
	s_waitcnt lgkmcnt(0)
	v_mfma_f32_16x16x32_bf16 v[60:63], v[128:131], v[176:179], v[60:63]
	v_mfma_f32_16x16x32_bf16 v[60:63], v[132:135], v[180:183], v[60:63]
	v_mfma_f32_16x16x32_bf16 v[56:59], v[136:139], v[176:179], v[56:59]
	v_mfma_f32_16x16x32_bf16 v[56:59], v[140:143], v[180:183], v[56:59]
	v_mfma_f32_16x16x32_bf16 v[44:47], v[128:131], v[184:187], v[44:47]
	v_mfma_f32_16x16x32_bf16 v[44:47], v[132:135], v[196:199], v[44:47]
	v_mfma_f32_16x16x32_bf16 v[40:43], v[136:139], v[184:187], v[40:43]
	v_mfma_f32_16x16x32_bf16 v[40:43], v[140:143], v[196:199], v[40:43]
	v_mfma_f32_16x16x32_bf16 v[28:31], v[128:131], v[200:203], v[28:31]
	v_mfma_f32_16x16x32_bf16 v[28:31], v[132:135], v[204:207], v[28:31]
	v_mfma_f32_16x16x32_bf16 v[24:27], v[136:139], v[200:203], v[24:27]
	v_mfma_f32_16x16x32_bf16 v[24:27], v[140:143], v[204:207], v[24:27]
	v_mfma_f32_16x16x32_bf16 v[12:15], v[128:131], v[208:211], v[12:15]
	v_mfma_f32_16x16x32_bf16 v[12:15], v[132:135], v[214:217], v[12:15]
	v_mfma_f32_16x16x32_bf16 v[8:11], v[136:139], v[208:211], v[8:11]
	v_mfma_f32_16x16x32_bf16 v[8:11], v[140:143], v[214:217], v[8:11]
	v_mfma_f32_16x16x32_bf16 v[52:55], v[144:147], v[176:179], v[52:55]
	v_mfma_f32_16x16x32_bf16 v[52:55], v[148:151], v[180:183], v[52:55]
	v_mfma_f32_16x16x32_bf16 v[48:51], v[168:171], v[176:179], v[48:51]
	v_mfma_f32_16x16x32_bf16 v[48:51], v[172:175], v[180:183], v[48:51]
	v_mfma_f32_16x16x32_bf16 v[36:39], v[144:147], v[184:187], v[36:39]
	v_mfma_f32_16x16x32_bf16 v[36:39], v[148:151], v[196:199], v[36:39]
	v_mfma_f32_16x16x32_bf16 v[32:35], v[168:171], v[184:187], v[32:35]
	v_mfma_f32_16x16x32_bf16 v[32:35], v[172:175], v[196:199], v[32:35]
	v_mfma_f32_16x16x32_bf16 v[20:23], v[144:147], v[200:203], v[20:23]
	v_mfma_f32_16x16x32_bf16 v[20:23], v[148:151], v[204:207], v[20:23]
	v_mfma_f32_16x16x32_bf16 v[16:19], v[168:171], v[200:203], v[16:19]
	v_mfma_f32_16x16x32_bf16 v[16:19], v[172:175], v[204:207], v[16:19]
	v_mfma_f32_16x16x32_bf16 v[4:7], v[144:147], v[208:211], v[4:7]
	v_mfma_f32_16x16x32_bf16 v[4:7], v[148:151], v[214:217], v[4:7]
	v_mfma_f32_16x16x32_bf16 v[0:3], v[168:171], v[208:211], v[0:3]
	v_mfma_f32_16x16x32_bf16 v[0:3], v[172:175], v[214:217], v[0:3]
	s_setprio 0
	s_barrier
	s_add_i32 s33, 0, 0x18000
	s_add_i32 s73, 0, 0x1c000
	v_add_u32_e32 v140, s33, v189
	v_add_u32_e32 v172, s73, v189
	ds_read_b128 v[128:131], v140
	ds_read_b128 v[132:135], v140 offset:1024
	ds_read_b128 v[136:139], v140 offset:2048
	ds_read_b128 v[140:143], v140 offset:3072
	ds_read_b128 v[144:147], v172
	ds_read_b128 v[148:151], v172 offset:1024
	ds_read_b128 v[168:171], v172 offset:2048
	ds_read_b128 v[172:175], v172 offset:3072
	s_add_u32 s54, s54, 0x160000
	s_addc_u32 s55, s55, 0
	s_mov_b32 m0, s58
	v_lshl_add_u64 v[226:227], s[54:55], 0, v[152:153]
	ds_read_b128 v[176:179], v193 offset:32768
	ds_read_b128 v[180:183], v193 offset:33792
	ds_read_b128 v[184:187], v193 offset:34816
	ds_read_b128 v[196:199], v193 offset:35840
	ds_read_b128 v[200:203], v193 offset:36864
	ds_read_b128 v[204:207], v193 offset:37888
	ds_read_b128 v[208:211], v193 offset:38912
	ds_read_b128 v[214:217], v193 offset:39936
	global_load_lds_dwordx4 v[226:227], off
	v_lshl_add_u64 v[226:227], s[54:55], 0, v[156:157]
	s_mov_b32 m0, s59
	s_nop 0
	global_load_lds_dwordx4 v[226:227], off
	s_waitcnt vmcnt(8)
	s_waitcnt lgkmcnt(0)
	s_barrier
	s_setprio 1
	s_waitcnt lgkmcnt(0)
	v_mfma_f32_16x16x32_bf16 v[124:127], v[128:131], v[176:179], v[124:127]
	v_mfma_f32_16x16x32_bf16 v[124:127], v[132:135], v[180:183], v[124:127]
	v_mfma_f32_16x16x32_bf16 v[120:123], v[136:139], v[176:179], v[120:123]
	v_mfma_f32_16x16x32_bf16 v[120:123], v[140:143], v[180:183], v[120:123]
	v_mfma_f32_16x16x32_bf16 v[108:111], v[128:131], v[184:187], v[108:111]
	v_mfma_f32_16x16x32_bf16 v[108:111], v[132:135], v[196:199], v[108:111]
	v_mfma_f32_16x16x32_bf16 v[104:107], v[136:139], v[184:187], v[104:107]
	v_mfma_f32_16x16x32_bf16 v[104:107], v[140:143], v[196:199], v[104:107]
	v_mfma_f32_16x16x32_bf16 v[92:95], v[128:131], v[200:203], v[92:95]
	v_mfma_f32_16x16x32_bf16 v[92:95], v[132:135], v[204:207], v[92:95]
	v_mfma_f32_16x16x32_bf16 v[88:91], v[136:139], v[200:203], v[88:91]
	v_mfma_f32_16x16x32_bf16 v[88:91], v[140:143], v[204:207], v[88:91]
	v_mfma_f32_16x16x32_bf16 v[76:79], v[128:131], v[208:211], v[76:79]
	v_mfma_f32_16x16x32_bf16 v[76:79], v[132:135], v[214:217], v[76:79]
	v_mfma_f32_16x16x32_bf16 v[72:75], v[136:139], v[208:211], v[72:75]
	v_mfma_f32_16x16x32_bf16 v[72:75], v[140:143], v[214:217], v[72:75]
	v_mfma_f32_16x16x32_bf16 v[116:119], v[144:147], v[176:179], v[116:119]
	v_mfma_f32_16x16x32_bf16 v[116:119], v[148:151], v[180:183], v[116:119]
	v_mfma_f32_16x16x32_bf16 v[112:115], v[168:171], v[176:179], v[112:115]
	v_mfma_f32_16x16x32_bf16 v[112:115], v[172:175], v[180:183], v[112:115]
	v_mfma_f32_16x16x32_bf16 v[100:103], v[144:147], v[184:187], v[100:103]
	v_mfma_f32_16x16x32_bf16 v[100:103], v[148:151], v[196:199], v[100:103]
	v_mfma_f32_16x16x32_bf16 v[96:99], v[168:171], v[184:187], v[96:99]
	v_mfma_f32_16x16x32_bf16 v[96:99], v[172:175], v[196:199], v[96:99]
	v_mfma_f32_16x16x32_bf16 v[84:87], v[144:147], v[200:203], v[84:87]
	v_mfma_f32_16x16x32_bf16 v[84:87], v[148:151], v[204:207], v[84:87]
	v_mfma_f32_16x16x32_bf16 v[80:83], v[168:171], v[200:203], v[80:83]
	v_mfma_f32_16x16x32_bf16 v[80:83], v[172:175], v[204:207], v[80:83]
	v_mfma_f32_16x16x32_bf16 v[68:71], v[144:147], v[208:211], v[68:71]
	v_mfma_f32_16x16x32_bf16 v[68:71], v[148:151], v[214:217], v[68:71]
	v_mfma_f32_16x16x32_bf16 v[64:67], v[168:171], v[208:211], v[64:67]
	v_mfma_f32_16x16x32_bf16 v[64:67], v[172:175], v[214:217], v[64:67]
	s_setprio 0
	s_barrier
; #define PG8_STAGE(bufoff, gbase, voff) do { _Pragma("unroll") for (int _i = 0; _i < 2; ++_i) \
;         __builtin_amdgcn_global_load_lds((const unsigned*)((const char*)(gbase) + (voff)[_i]), (PG8_LAS unsigned*)(lds + (bufoff) + ldsw + _i * 8192), 16, 0, 0); } while (0)
; #define PG8_WAIT_V(n) asm volatile("s_waitcnt vmcnt(" #n ")" ::: "memory")
; #define PG8_WAIT_L(n) asm volatile("s_waitcnt lgkmcnt(" #n ")" ::: "memory")
; #define PG8_BAR __builtin_amdgcn_s_barrier()
; #define PG8_SCHED __builtin_amdgcn_sched_barrier(0)
;     ...
;             PG8_LDA(At, 1, 1); PG8_STAGE(PG8_SB(1, 0), b3, voffB); PG8_STAGE(PG8_SB(1, 1), b3 + hstep, voffB); PG8_STAGE(PG8_SA(1, 0), a3, voffA);
;             PG8_WAIT_V(8); PG8_WAIT_L(0); PG8_BAR; PG8_MMA(1, 0, At, B0); PG8_MMA(1, 1, At, B1); PG8_BAR; PG8_SCHED;
;     ...
;         if constexpr (ALIGN_EPI) { if (wr == 0) PG8_BAR; }
	s_add_i32 s33, s33, s19
	v_lshl_add_u64 v[218:219], v[218:219], 0, s[24:25]
	s_mov_b32 m0, s33
	ds_read_b128 v[176:179], v193 offset:49152
	ds_read_b128 v[180:183], v193 offset:50176
	ds_read_b128 v[184:187], v193 offset:51200
	ds_read_b128 v[196:199], v193 offset:52224
	ds_read_b128 v[200:203], v193 offset:53248
	ds_read_b128 v[204:207], v193 offset:54272
	ds_read_b128 v[208:211], v193 offset:55296
	ds_read_b128 v[214:217], v193 offset:56320
	global_load_lds_dwordx4 v[218:219], off
	s_add_i32 m0, s33, 0x2000
	s_add_u32 s52, s52, 0x160080
	v_lshl_add_u64 v[218:219], v[220:221], 0, s[24:25]
	s_addc_u32 s53, s53, 0
	s_add_i32 s33, s73, s19
	global_load_lds_dwordx4 v[218:219], off
	v_lshl_add_u64 v[218:219], s[52:53], 0, v[154:155]
	s_mov_b32 m0, s33
	s_nop 0
	global_load_lds_dwordx4 v[218:219], off
	v_lshl_add_u64 v[218:219], s[52:53], 0, v[158:159]
	s_add_i32 m0, s33, 0x2000
	s_nop 0
	global_load_lds_dwordx4 v[218:219], off
	v_lshl_add_u64 v[218:219], v[222:223], 0, s[24:25]
	s_mov_b32 m0, s61
	s_nop 0
	global_load_lds_dwordx4 v[218:219], off
	v_lshl_add_u64 v[218:219], v[224:225], 0, s[24:25]
	s_mov_b32 m0, s62
	s_nop 0
	global_load_lds_dwordx4 v[218:219], off
	s_waitcnt vmcnt(8)
	s_waitcnt lgkmcnt(0)
	s_barrier
	s_setprio 1
	s_waitcnt lgkmcnt(0)
	v_mfma_f32_16x16x32_bf16 v[60:63], v[128:131], v[176:179], v[60:63]
	v_mfma_f32_16x16x32_bf16 v[60:63], v[132:135], v[180:183], v[60:63]
	v_mfma_f32_16x16x32_bf16 v[56:59], v[136:139], v[176:179], v[56:59]
	v_mfma_f32_16x16x32_bf16 v[56:59], v[140:143], v[180:183], v[56:59]
	v_mfma_f32_16x16x32_bf16 v[44:47], v[128:131], v[184:187], v[44:47]
	v_mfma_f32_16x16x32_bf16 v[44:47], v[132:135], v[196:199], v[44:47]
	v_mfma_f32_16x16x32_bf16 v[40:43], v[136:139], v[184:187], v[40:43]
	v_mfma_f32_16x16x32_bf16 v[40:43], v[140:143], v[196:199], v[40:43]
	v_mfma_f32_16x16x32_bf16 v[28:31], v[128:131], v[200:203], v[28:31]
	v_mfma_f32_16x16x32_bf16 v[28:31], v[132:135], v[204:207], v[28:31]
	v_mfma_f32_16x16x32_bf16 v[24:27], v[136:139], v[200:203], v[24:27]
	v_mfma_f32_16x16x32_bf16 v[24:27], v[140:143], v[204:207], v[24:27]
	v_mfma_f32_16x16x32_bf16 v[12:15], v[128:131], v[208:211], v[12:15]
	v_mfma_f32_16x16x32_bf16 v[12:15], v[132:135], v[214:217], v[12:15]
	v_mfma_f32_16x16x32_bf16 v[8:11], v[136:139], v[208:211], v[8:11]
	v_mfma_f32_16x16x32_bf16 v[8:11], v[140:143], v[214:217], v[8:11]
	v_mfma_f32_16x16x32_bf16 v[52:55], v[144:147], v[176:179], v[52:55]
	v_mfma_f32_16x16x32_bf16 v[52:55], v[148:151], v[180:183], v[52:55]
	v_mfma_f32_16x16x32_bf16 v[48:51], v[168:171], v[176:179], v[48:51]
	v_mfma_f32_16x16x32_bf16 v[48:51], v[172:175], v[180:183], v[48:51]
	v_mfma_f32_16x16x32_bf16 v[36:39], v[144:147], v[184:187], v[36:39]
	v_mfma_f32_16x16x32_bf16 v[36:39], v[148:151], v[196:199], v[36:39]
	v_mfma_f32_16x16x32_bf16 v[32:35], v[168:171], v[184:187], v[32:35]
	v_mfma_f32_16x16x32_bf16 v[32:35], v[172:175], v[196:199], v[32:35]
	v_mfma_f32_16x16x32_bf16 v[20:23], v[144:147], v[200:203], v[20:23]
	v_mfma_f32_16x16x32_bf16 v[20:23], v[148:151], v[204:207], v[20:23]
	v_mfma_f32_16x16x32_bf16 v[16:19], v[168:171], v[200:203], v[16:19]
	v_mfma_f32_16x16x32_bf16 v[16:19], v[172:175], v[204:207], v[16:19]
	v_mfma_f32_16x16x32_bf16 v[4:7], v[144:147], v[208:211], v[4:7]
	v_mfma_f32_16x16x32_bf16 v[4:7], v[148:151], v[214:217], v[4:7]
	v_mfma_f32_16x16x32_bf16 v[0:3], v[168:171], v[208:211], v[0:3]
	v_mfma_f32_16x16x32_bf16 v[0:3], v[172:175], v[214:217], v[0:3]
	s_setprio 0
	s_barrier
	s_add_i32 s72, s72, 2
	s_add_u32 s50, s50, 0x100
	s_addc_u32 s51, s51, 0
	s_add_u32 s34, s34, 0x100
	s_addc_u32 s35, s35, 0
	s_cmpk_gt_u32 s72, 0x55
	s_cbranch_scc0 .LBB0_335
	s_and_b64 vcc, exec, s[44:45]
	s_cbranch_vccz .LBB0_338
	s_barrier

; #define PG8_STAGE(bufoff, gbase, voff) do { _Pragma("unroll") for (int _i = 0; _i < 2; ++_i) \
;         __builtin_amdgcn_global_load_lds((const unsigned*)((const char*)(gbase) + (voff)[_i]), (PG8_LAS unsigned*)(lds + (bufoff) + ldsw + _i * 8192), 16, 0, 0); } while (0)
; #define PG8_WAIT_V(n) asm volatile("s_waitcnt vmcnt(" #n ")" ::: "memory")
; #define PG8_WAIT_L(n) asm volatile("s_waitcnt lgkmcnt(" #n ")" ::: "memory")
; #define PG8_BAR __builtin_amdgcn_s_barrier()
; #define PG8_SCHED __builtin_amdgcn_sched_barrier(0)
;     ...
;             const char* a1 = cA + (size_t)(t + 1) * kstep;
;             const char* a2 = last ? nA : cA + (size_t)(t + 2) * kstep; const char* b2 = last ? nB : cB + (size_t)(t + 2) * kstep;
;             const char* a3 = a2 + kstep; const char* b3 = b2 + kstep;
;             if (last && has_next) S.a_ready(nxt);
;             if (last) E.pre(pre, cur, wr, fr);
;             if constexpr (MIDK > 0) { if (t == MIDK / BK) E.mid(acc, cur, wr, wc, fr, fq); }
;             if constexpr (SP2) {
;             PG8_LDB(B0, 0, 0); PG8_LDB(B1, 0, 1); PG8_SCHED; PG8_LDA(At, 0, 0); PG8_STAGE(PG8_SA(1, 1), a1 + hstep, voffA);
;             PG8_WAIT_V(8); PG8_WAIT_L(0); PG8_BAR; PG8_MMA(0, 0, At, B0); PG8_MMA(0, 1, At, B1); PG8_BAR; PG8_SCHED;
;             PG8_LDA(At, 0, 1); PG8_STAGE(PG8_SB(0, 0), b2, voffB); PG8_STAGE(PG8_SB(0, 1), b2 + hstep, voffB); PG8_STAGE(PG8_SA(0, 0), a2, voffA);
;             PG8_WAIT_V(8); PG8_WAIT_L(0); PG8_BAR; PG8_MMA(1, 0, At, B0); PG8_MMA(1, 1, At, B1); PG8_BAR; PG8_SCHED;
.LBB0_432:
	v_add_u32_e32 v142, s91, v205
	v_add_u32_e32 v146, s92, v205
	ds_read_b128 v[130:133], v142
	ds_read_b128 v[134:137], v142 offset:1024
	s_waitcnt lgkmcnt(0)
	ds_read_b128 v[138:141], v142 offset:2048
	ds_read_b128 v[142:145], v142 offset:3072
	ds_read_b128 v[188:191], v146
	ds_read_b128 v[192:195], v146 offset:1024
	ds_read_b128 v[196:199], v146 offset:2048
	ds_read_b128 v[200:203], v146 offset:3072
	s_add_u32 s33, s70, 0xfff80080
	s_addc_u32 s74, s71, -1
	s_and_b64 s[72:73], s[72:73], exec
	s_cselect_b32 s75, s18, s74
	s_cselect_b32 s74, s19, s33
	s_cselect_b32 s73, s34, s61
	s_cselect_b32 s72, s35, s10
	v_lshl_add_u64 v[146:147], s[70:71], 0, v[162:163]
	s_add_i32 m0, s69, 0xc000
	ds_read_b128 v[214:217], v159
	ds_read_b128 v[218:221], v159 offset:1024
	ds_read_b128 v[222:225], v159 offset:2048
	ds_read_b128 v[226:229], v159 offset:3072
	ds_read_b128 v[230:233], v159 offset:4096
	ds_read_b128 v[234:237], v159 offset:5120
	ds_read_b128 v[238:241], v159 offset:6144
	ds_read_b128 v[242:245], v159 offset:7168
	global_load_lds_dwordx4 v[146:147], off
	v_lshl_add_u64 v[146:147], s[70:71], 0, v[164:165]
	s_add_i32 m0, s69, 0xe000
	s_nop 0
	global_load_lds_dwordx4 v[146:147], off
	s_waitcnt vmcnt(8)
	s_waitcnt lgkmcnt(0)
	s_barrier
	s_setprio 1
	s_waitcnt lgkmcnt(0)
	v_mfma_f32_16x16x32_bf16 v[124:127], v[130:133], v[214:217], v[124:127]
	v_mfma_f32_16x16x32_bf16 v[124:127], v[134:137], v[218:221], v[124:127]
	v_mfma_f32_16x16x32_bf16 v[120:123], v[138:141], v[214:217], v[120:123]
	v_mfma_f32_16x16x32_bf16 v[120:123], v[142:145], v[218:221], v[120:123]
	v_mfma_f32_16x16x32_bf16 v[108:111], v[130:133], v[222:225], v[108:111]
	v_mfma_f32_16x16x32_bf16 v[108:111], v[134:137], v[226:229], v[108:111]
	v_mfma_f32_16x16x32_bf16 v[104:107], v[138:141], v[222:225], v[104:107]
	v_mfma_f32_16x16x32_bf16 v[104:107], v[142:145], v[226:229], v[104:107]
	v_mfma_f32_16x16x32_bf16 v[92:95], v[130:133], v[230:233], v[92:95]
	v_mfma_f32_16x16x32_bf16 v[92:95], v[134:137], v[234:237], v[92:95]
	v_mfma_f32_16x16x32_bf16 v[88:91], v[138:141], v[230:233], v[88:91]
	v_mfma_f32_16x16x32_bf16 v[88:91], v[142:145], v[234:237], v[88:91]
	v_mfma_f32_16x16x32_bf16 v[76:79], v[130:133], v[238:241], v[76:79]
	v_mfma_f32_16x16x32_bf16 v[76:79], v[134:137], v[242:245], v[76:79]
	v_mfma_f32_16x16x32_bf16 v[72:75], v[138:141], v[238:241], v[72:75]
	v_mfma_f32_16x16x32_bf16 v[72:75], v[142:145], v[242:245], v[72:75]
	v_mfma_f32_16x16x32_bf16 v[116:119], v[188:191], v[214:217], v[116:119]
	v_mfma_f32_16x16x32_bf16 v[116:119], v[192:195], v[218:221], v[116:119]
	v_mfma_f32_16x16x32_bf16 v[112:115], v[196:199], v[214:217], v[112:115]
	v_mfma_f32_16x16x32_bf16 v[112:115], v[200:203], v[218:221], v[112:115]
	v_mfma_f32_16x16x32_bf16 v[100:103], v[188:191], v[222:225], v[100:103]
	v_mfma_f32_16x16x32_bf16 v[100:103], v[192:195], v[226:229], v[100:103]
	v_mfma_f32_16x16x32_bf16 v[96:99], v[196:199], v[222:225], v[96:99]
	v_mfma_f32_16x16x32_bf16 v[96:99], v[200:203], v[226:229], v[96:99]
	v_mfma_f32_16x16x32_bf16 v[84:87], v[188:191], v[230:233], v[84:87]
	v_mfma_f32_16x16x32_bf16 v[84:87], v[192:195], v[234:237], v[84:87]
	v_mfma_f32_16x16x32_bf16 v[80:83], v[196:199], v[230:233], v[80:83]
	v_mfma_f32_16x16x32_bf16 v[80:83], v[200:203], v[234:237], v[80:83]
	v_mfma_f32_16x16x32_bf16 v[68:71], v[188:191], v[238:241], v[68:71]
	v_mfma_f32_16x16x32_bf16 v[68:71], v[192:195], v[242:245], v[68:71]
	v_mfma_f32_16x16x32_bf16 v[64:67], v[196:199], v[238:241], v[64:67]
	v_mfma_f32_16x16x32_bf16 v[64:67], v[200:203], v[242:245], v[64:67]
	s_setprio 0
	s_barrier
	s_add_i32 s33, s91, s82
	v_lshl_add_u64 v[146:147], s[72:73], 0, v[150:151]
	s_mov_b32 m0, s33
	ds_read_b128 v[214:217], v159 offset:16384
	ds_read_b128 v[218:221], v159 offset:17408
	ds_read_b128 v[222:225], v159 offset:18432
	ds_read_b128 v[226:229], v159 offset:19456
	ds_read_b128 v[230:233], v159 offset:20480
	ds_read_b128 v[234:237], v159 offset:21504
	ds_read_b128 v[238:241], v159 offset:22528
	ds_read_b128 v[242:245], v159 offset:23552
	global_load_lds_dwordx4 v[146:147], off
	s_add_i32 m0, s33, 0x2000
	s_add_u32 s94, s72, 0x80000
	v_lshl_add_u64 v[246:247], s[72:73], 0, v[154:155]
	s_addc_u32 s95, s73, 0
	s_add_i32 s33, s92, s82
	global_load_lds_dwordx4 v[246:247], off
	v_lshl_add_u64 v[248:249], s[94:95], 0, v[150:151]
	s_mov_b32 m0, s33
	v_lshl_add_u64 v[250:251], s[74:75], 0, v[152:153]
	global_load_lds_dwordx4 v[248:249], off
	v_lshl_add_u64 v[248:249], s[94:95], 0, v[154:155]
	s_add_i32 m0, s33, 0x2000
	s_nop 0
	global_load_lds_dwordx4 v[248:249], off
	v_lshl_add_u64 v[248:249], s[74:75], 0, v[148:149]
	s_mov_b32 m0, s69
	s_nop 0
	global_load_lds_dwordx4 v[248:249], off
	s_mov_b32 m0, s83
	s_nop 0
	global_load_lds_dwordx4 v[250:251], off
	s_waitcnt vmcnt(8)
	s_waitcnt lgkmcnt(0)
	s_barrier
; #define PG8_STAGE(bufoff, gbase, voff) do { _Pragma("unroll") for (int _i = 0; _i < 2; ++_i) \
;         __builtin_amdgcn_global_load_lds((const unsigned*)((const char*)(gbase) + (voff)[_i]), (PG8_LAS unsigned*)(lds + (bufoff) + ldsw + _i * 8192), 16, 0, 0); } while (0)
; #define PG8_WAIT_V(n) asm volatile("s_waitcnt vmcnt(" #n ")" ::: "memory")
; #define PG8_WAIT_L(n) asm volatile("s_waitcnt lgkmcnt(" #n ")" ::: "memory")
; #define PG8_BAR __builtin_amdgcn_s_barrier()
; #define PG8_SCHED __builtin_amdgcn_sched_barrier(0)
;     ...
;             PG8_WAIT_V(8); PG8_WAIT_L(0); PG8_BAR; PG8_MMA(1, 0, At, B0); PG8_MMA(1, 1, At, B1); PG8_BAR; PG8_SCHED;
;             PG8_LDB(B0, 1, 0); PG8_LDB(B1, 1, 1); PG8_SCHED; PG8_LDA(At, 1, 0); PG8_STAGE(PG8_SA(0, 1), a2 + hstep, voffA);
;             PG8_WAIT_V(8); PG8_WAIT_L(0); PG8_BAR; PG8_MMA(0, 0, At, B0); PG8_MMA(0, 1, At, B1); PG8_BAR; PG8_SCHED;
	s_setprio 1
	s_waitcnt lgkmcnt(0)
	v_mfma_f32_16x16x32_bf16 v[60:63], v[130:133], v[214:217], v[60:63]
	v_mfma_f32_16x16x32_bf16 v[60:63], v[134:137], v[218:221], v[60:63]
	v_mfma_f32_16x16x32_bf16 v[56:59], v[138:141], v[214:217], v[56:59]
	v_mfma_f32_16x16x32_bf16 v[56:59], v[142:145], v[218:221], v[56:59]
	v_mfma_f32_16x16x32_bf16 v[44:47], v[130:133], v[222:225], v[44:47]
	v_mfma_f32_16x16x32_bf16 v[44:47], v[134:137], v[226:229], v[44:47]
	v_mfma_f32_16x16x32_bf16 v[40:43], v[138:141], v[222:225], v[40:43]
	v_mfma_f32_16x16x32_bf16 v[40:43], v[142:145], v[226:229], v[40:43]
	v_mfma_f32_16x16x32_bf16 v[28:31], v[130:133], v[230:233], v[28:31]
	v_mfma_f32_16x16x32_bf16 v[28:31], v[134:137], v[234:237], v[28:31]
	v_mfma_f32_16x16x32_bf16 v[24:27], v[138:141], v[230:233], v[24:27]
	v_mfma_f32_16x16x32_bf16 v[24:27], v[142:145], v[234:237], v[24:27]
	v_mfma_f32_16x16x32_bf16 v[12:15], v[130:133], v[238:241], v[12:15]
	v_mfma_f32_16x16x32_bf16 v[12:15], v[134:137], v[242:245], v[12:15]
	v_mfma_f32_16x16x32_bf16 v[8:11], v[138:141], v[238:241], v[8:11]
	v_mfma_f32_16x16x32_bf16 v[8:11], v[142:145], v[242:245], v[8:11]
	v_mfma_f32_16x16x32_bf16 v[52:55], v[188:191], v[214:217], v[52:55]
	v_mfma_f32_16x16x32_bf16 v[52:55], v[192:195], v[218:221], v[52:55]
	v_mfma_f32_16x16x32_bf16 v[48:51], v[196:199], v[214:217], v[48:51]
	v_mfma_f32_16x16x32_bf16 v[48:51], v[200:203], v[218:221], v[48:51]
	v_mfma_f32_16x16x32_bf16 v[36:39], v[188:191], v[222:225], v[36:39]
	v_mfma_f32_16x16x32_bf16 v[36:39], v[192:195], v[226:229], v[36:39]
	v_mfma_f32_16x16x32_bf16 v[32:35], v[196:199], v[222:225], v[32:35]
	v_mfma_f32_16x16x32_bf16 v[32:35], v[200:203], v[226:229], v[32:35]
	v_mfma_f32_16x16x32_bf16 v[20:23], v[188:191], v[230:233], v[20:23]
	v_mfma_f32_16x16x32_bf16 v[20:23], v[192:195], v[234:237], v[20:23]
	v_mfma_f32_16x16x32_bf16 v[16:19], v[196:199], v[230:233], v[16:19]
	v_mfma_f32_16x16x32_bf16 v[16:19], v[200:203], v[234:237], v[16:19]
	v_mfma_f32_16x16x32_bf16 v[4:7], v[188:191], v[238:241], v[4:7]
	v_mfma_f32_16x16x32_bf16 v[4:7], v[192:195], v[242:245], v[4:7]
	v_mfma_f32_16x16x32_bf16 v[0:3], v[196:199], v[238:241], v[0:3]
	v_mfma_f32_16x16x32_bf16 v[0:3], v[200:203], v[242:245], v[0:3]
	s_setprio 0
	s_barrier
	s_add_i32 s33, 0, 0x18000
	s_add_i32 s94, 0, 0x1c000
	v_add_u32_e32 v142, s33, v205
	v_add_u32_e32 v156, s94, v205
	ds_read_b128 v[130:133], v142
	ds_read_b128 v[134:137], v142 offset:1024
	ds_read_b128 v[138:141], v142 offset:2048
	ds_read_b128 v[142:145], v142 offset:3072
	ds_read_b128 v[188:191], v156
	ds_read_b128 v[192:195], v156 offset:1024
	ds_read_b128 v[196:199], v156 offset:2048
	ds_read_b128 v[200:203], v156 offset:3072
	s_add_u32 s74, s74, 0x80000
	s_addc_u32 s75, s75, 0
	s_mov_b32 m0, s84
	v_lshl_add_u64 v[252:253], s[74:75], 0, v[148:149]
	ds_read_b128 v[214:217], v159 offset:32768
	ds_read_b128 v[218:221], v159 offset:33792
	ds_read_b128 v[222:225], v159 offset:34816
	ds_read_b128 v[226:229], v159 offset:35840
	ds_read_b128 v[230:233], v159 offset:36864
	ds_read_b128 v[234:237], v159 offset:37888
	ds_read_b128 v[238:241], v159 offset:38912
	ds_read_b128 v[242:245], v159 offset:39936
	global_load_lds_dwordx4 v[252:253], off
	v_lshl_add_u64 v[252:253], s[74:75], 0, v[152:153]
	s_mov_b32 m0, s85
	s_nop 0
	global_load_lds_dwordx4 v[252:253], off
	s_waitcnt vmcnt(8)
	s_waitcnt lgkmcnt(0)
	s_barrier
	s_setprio 1
	s_waitcnt lgkmcnt(0)
	v_mfma_f32_16x16x32_bf16 v[124:127], v[130:133], v[214:217], v[124:127]
	v_mfma_f32_16x16x32_bf16 v[124:127], v[134:137], v[218:221], v[124:127]
	v_mfma_f32_16x16x32_bf16 v[120:123], v[138:141], v[214:217], v[120:123]
	v_mfma_f32_16x16x32_bf16 v[120:123], v[142:145], v[218:221], v[120:123]
	v_mfma_f32_16x16x32_bf16 v[108:111], v[130:133], v[222:225], v[108:111]
	v_mfma_f32_16x16x32_bf16 v[108:111], v[134:137], v[226:229], v[108:111]
	v_mfma_f32_16x16x32_bf16 v[104:107], v[138:141], v[222:225], v[104:107]
	v_mfma_f32_16x16x32_bf16 v[104:107], v[142:145], v[226:229], v[104:107]
	v_mfma_f32_16x16x32_bf16 v[92:95], v[130:133], v[230:233], v[92:95]
	v_mfma_f32_16x16x32_bf16 v[92:95], v[134:137], v[234:237], v[92:95]
	v_mfma_f32_16x16x32_bf16 v[88:91], v[138:141], v[230:233], v[88:91]
	v_mfma_f32_16x16x32_bf16 v[88:91], v[142:145], v[234:237], v[88:91]
	v_mfma_f32_16x16x32_bf16 v[76:79], v[130:133], v[238:241], v[76:79]
	v_mfma_f32_16x16x32_bf16 v[76:79], v[134:137], v[242:245], v[76:79]
	v_mfma_f32_16x16x32_bf16 v[72:75], v[138:141], v[238:241], v[72:75]
	v_mfma_f32_16x16x32_bf16 v[72:75], v[142:145], v[242:245], v[72:75]
	v_mfma_f32_16x16x32_bf16 v[116:119], v[188:191], v[214:217], v[116:119]
	v_mfma_f32_16x16x32_bf16 v[116:119], v[192:195], v[218:221], v[116:119]
	v_mfma_f32_16x16x32_bf16 v[112:115], v[196:199], v[214:217], v[112:115]
	v_mfma_f32_16x16x32_bf16 v[112:115], v[200:203], v[218:221], v[112:115]
	v_mfma_f32_16x16x32_bf16 v[100:103], v[188:191], v[222:225], v[100:103]
	v_mfma_f32_16x16x32_bf16 v[100:103], v[192:195], v[226:229], v[100:103]
	v_mfma_f32_16x16x32_bf16 v[96:99], v[196:199], v[222:225], v[96:99]
	v_mfma_f32_16x16x32_bf16 v[96:99], v[200:203], v[226:229], v[96:99]
	v_mfma_f32_16x16x32_bf16 v[84:87], v[188:191], v[230:233], v[84:87]
	v_mfma_f32_16x16x32_bf16 v[84:87], v[192:195], v[234:237], v[84:87]
	v_mfma_f32_16x16x32_bf16 v[80:83], v[196:199], v[230:233], v[80:83]
	v_mfma_f32_16x16x32_bf16 v[80:83], v[200:203], v[234:237], v[80:83]
	v_mfma_f32_16x16x32_bf16 v[68:71], v[188:191], v[238:241], v[68:71]
	v_mfma_f32_16x16x32_bf16 v[68:71], v[192:195], v[242:245], v[68:71]
	v_mfma_f32_16x16x32_bf16 v[64:67], v[196:199], v[238:241], v[64:67]
	v_mfma_f32_16x16x32_bf16 v[64:67], v[200:203], v[242:245], v[64:67]
	s_setprio 0
	s_barrier
; #define PG8_STAGE(bufoff, gbase, voff) do { _Pragma("unroll") for (int _i = 0; _i < 2; ++_i) \
;         __builtin_amdgcn_global_load_lds((const unsigned*)((const char*)(gbase) + (voff)[_i]), (PG8_LAS unsigned*)(lds + (bufoff) + ldsw + _i * 8192), 16, 0, 0); } while (0)
; #define PG8_WAIT_V(n) asm volatile("s_waitcnt vmcnt(" #n ")" ::: "memory")
; #define PG8_WAIT_L(n) asm volatile("s_waitcnt lgkmcnt(" #n ")" ::: "memory")
; #define PG8_BAR __builtin_amdgcn_s_barrier()
; #define PG8_SCHED __builtin_amdgcn_sched_barrier(0)
;     ...
;             PG8_LDA(At, 1, 1); PG8_STAGE(PG8_SB(1, 0), b3, voffB); PG8_STAGE(PG8_SB(1, 1), b3 + hstep, voffB); PG8_STAGE(PG8_SA(1, 0), a3, voffA);
;             PG8_WAIT_V(8); PG8_WAIT_L(0); PG8_BAR; PG8_MMA(1, 0, At, B0); PG8_MMA(1, 1, At, B1); PG8_BAR; PG8_SCHED;
	s_add_i32 s33, s33, s82
	v_lshl_add_u64 v[146:147], v[146:147], 0, s[50:51]
	s_mov_b32 m0, s33
	ds_read_b128 v[214:217], v159 offset:49152
	ds_read_b128 v[218:221], v159 offset:50176
	ds_read_b128 v[222:225], v159 offset:51200
	ds_read_b128 v[226:229], v159 offset:52224
	ds_read_b128 v[230:233], v159 offset:53248
	ds_read_b128 v[234:237], v159 offset:54272
	ds_read_b128 v[238:241], v159 offset:55296
	ds_read_b128 v[242:245], v159 offset:56320
	global_load_lds_dwordx4 v[146:147], off
	s_add_i32 m0, s33, 0x2000
	s_add_u32 s72, s72, 0x80080
	v_lshl_add_u64 v[146:147], v[246:247], 0, s[50:51]
	s_addc_u32 s73, s73, 0
	s_add_i32 s33, s94, s82
	global_load_lds_dwordx4 v[146:147], off
	v_lshl_add_u64 v[146:147], s[72:73], 0, v[150:151]
	s_mov_b32 m0, s33
	s_nop 0
	global_load_lds_dwordx4 v[146:147], off
	v_lshl_add_u64 v[146:147], s[72:73], 0, v[154:155]
	s_add_i32 m0, s33, 0x2000
	s_nop 0
	global_load_lds_dwordx4 v[146:147], off
	v_lshl_add_u64 v[146:147], v[248:249], 0, s[50:51]
	s_mov_b32 m0, s86
	s_nop 0
	global_load_lds_dwordx4 v[146:147], off
	v_lshl_add_u64 v[146:147], v[250:251], 0, s[50:51]
	s_mov_b32 m0, s87
	s_nop 0
	global_load_lds_dwordx4 v[146:147], off
	s_waitcnt vmcnt(8)
	s_waitcnt lgkmcnt(0)
	s_barrier
	s_setprio 1
	s_waitcnt lgkmcnt(0)
	v_mfma_f32_16x16x32_bf16 v[60:63], v[130:133], v[214:217], v[60:63]
	v_mfma_f32_16x16x32_bf16 v[60:63], v[134:137], v[218:221], v[60:63]
	v_mfma_f32_16x16x32_bf16 v[56:59], v[138:141], v[214:217], v[56:59]
	v_mfma_f32_16x16x32_bf16 v[56:59], v[142:145], v[218:221], v[56:59]
	v_mfma_f32_16x16x32_bf16 v[44:47], v[130:133], v[222:225], v[44:47]
	v_mfma_f32_16x16x32_bf16 v[44:47], v[134:137], v[226:229], v[44:47]
	v_mfma_f32_16x16x32_bf16 v[40:43], v[138:141], v[222:225], v[40:43]
	v_mfma_f32_16x16x32_bf16 v[40:43], v[142:145], v[226:229], v[40:43]
	v_mfma_f32_16x16x32_bf16 v[28:31], v[130:133], v[230:233], v[28:31]
	v_mfma_f32_16x16x32_bf16 v[28:31], v[134:137], v[234:237], v[28:31]
	v_mfma_f32_16x16x32_bf16 v[24:27], v[138:141], v[230:233], v[24:27]
	v_mfma_f32_16x16x32_bf16 v[24:27], v[142:145], v[234:237], v[24:27]
	v_mfma_f32_16x16x32_bf16 v[12:15], v[130:133], v[238:241], v[12:15]
	v_mfma_f32_16x16x32_bf16 v[12:15], v[134:137], v[242:245], v[12:15]
	v_mfma_f32_16x16x32_bf16 v[8:11], v[138:141], v[238:241], v[8:11]
	v_mfma_f32_16x16x32_bf16 v[8:11], v[142:145], v[242:245], v[8:11]
	v_mfma_f32_16x16x32_bf16 v[52:55], v[188:191], v[214:217], v[52:55]
	v_mfma_f32_16x16x32_bf16 v[52:55], v[192:195], v[218:221], v[52:55]
	v_mfma_f32_16x16x32_bf16 v[48:51], v[196:199], v[214:217], v[48:51]
	v_mfma_f32_16x16x32_bf16 v[48:51], v[200:203], v[218:221], v[48:51]
	v_mfma_f32_16x16x32_bf16 v[36:39], v[188:191], v[222:225], v[36:39]
	v_mfma_f32_16x16x32_bf16 v[36:39], v[192:195], v[226:229], v[36:39]
	v_mfma_f32_16x16x32_bf16 v[32:35], v[196:199], v[222:225], v[32:35]
	v_mfma_f32_16x16x32_bf16 v[32:35], v[200:203], v[226:229], v[32:35]
	v_mfma_f32_16x16x32_bf16 v[20:23], v[188:191], v[230:233], v[20:23]
	v_mfma_f32_16x16x32_bf16 v[20:23], v[192:195], v[234:237], v[20:23]
	v_mfma_f32_16x16x32_bf16 v[16:19], v[196:199], v[230:233], v[16:19]
	v_mfma_f32_16x16x32_bf16 v[16:19], v[200:203], v[234:237], v[16:19]
	v_mfma_f32_16x16x32_bf16 v[4:7], v[188:191], v[238:241], v[4:7]
	v_mfma_f32_16x16x32_bf16 v[4:7], v[192:195], v[242:245], v[4:7]
	v_mfma_f32_16x16x32_bf16 v[0:3], v[196:199], v[238:241], v[0:3]
	v_mfma_f32_16x16x32_bf16 v[0:3], v[200:203], v[242:245], v[0:3]
	s_setprio 0
	s_barrier
	s_add_i32 s63, s63, 2
	s_add_u32 s70, s70, 0x100
	s_addc_u32 s71, s71, 0
	s_add_u32 s10, s10, 0x100
	s_addc_u32 s61, s61, 0
	s_cmp_gt_u32 s63, 29
	s_cbranch_scc1 .LBB0_435

; #define PG8_STAGE(bufoff, gbase, voff) do { _Pragma("unroll") for (int _i = 0; _i < 2; ++_i) \
;         __builtin_amdgcn_global_load_lds((const unsigned*)((const char*)(gbase) + (voff)[_i]), (PG8_LAS unsigned*)(lds + (bufoff) + ldsw + _i * 8192), 16, 0, 0); } while (0)
; #define PG8_WAIT_V(n) asm volatile("s_waitcnt vmcnt(" #n ")" ::: "memory")
; #define PG8_WAIT_L(n) asm volatile("s_waitcnt lgkmcnt(" #n ")" ::: "memory")
; #define PG8_BAR __builtin_amdgcn_s_barrier()
; #define PG8_SCHED __builtin_amdgcn_sched_barrier(0)
;     ...
;             const char* a1 = cA + (size_t)(t + 1) * kstep;
;             const char* a2 = last ? nA : cA + (size_t)(t + 2) * kstep; const char* b2 = last ? nB : cB + (size_t)(t + 2) * kstep;
;             const char* a3 = a2 + kstep; const char* b3 = b2 + kstep;
;             if (last && has_next) S.a_ready(nxt);
;             if (last) E.pre(pre, cur, wr, fr);
;             if constexpr (MIDK > 0) { if (t == MIDK / BK) E.mid(acc, cur, wr, wc, fr, fq); }
;             if constexpr (SP2) {
;             PG8_LDB(B0, 0, 0); PG8_LDB(B1, 0, 1); PG8_SCHED; PG8_LDA(At, 0, 0); PG8_STAGE(PG8_SA(1, 1), a1 + hstep, voffA);
;             PG8_WAIT_V(8); PG8_WAIT_L(0); PG8_BAR; PG8_MMA(0, 0, At, B0); PG8_MMA(0, 1, At, B1); PG8_BAR; PG8_SCHED;
;             PG8_LDA(At, 0, 1); PG8_STAGE(PG8_SB(0, 0), b2, voffB); PG8_STAGE(PG8_SB(0, 1), b2 + hstep, voffB); PG8_STAGE(PG8_SA(0, 0), a2, voffA);
;             PG8_WAIT_V(8); PG8_WAIT_L(0); PG8_BAR; PG8_MMA(1, 0, At, B0); PG8_MMA(1, 1, At, B1); PG8_BAR; PG8_SCHED;
.LBB0_666:
	v_add_u32_e32 v1, s70, v175
	s_add_u32 s33, s52, s54
	ds_read_b128 v[140:143], v1
	ds_read_b128 v[144:147], v1 offset:1024
	ds_read_b128 v[148:151], v1 offset:2048
	ds_read_b128 v[152:155], v1 offset:3072
	v_add_u32_e32 v1, s71, v175
	s_addc_u32 s58, s53, s55
	ds_read_b128 v[190:193], v1
	ds_read_b128 v[194:197], v1 offset:1024
	ds_read_b128 v[198:201], v1 offset:2048
	ds_read_b128 v[202:205], v1 offset:3072
	s_add_u32 s33, s33, 0x100
	s_addc_u32 s76, s58, 0
	s_and_b64 s[58:59], s[56:57], exec
	s_cselect_b32 s59, s34, s76
	s_cselect_b32 s58, s35, s33
	s_add_u32 s33, s73, s54
	s_addc_u32 s76, s74, s55
	s_and_b64 s[56:57], s[56:57], exec
	s_cselect_b32 s57, s45, s76
	s_cselect_b32 s56, s47, s33
	v_lshl_add_u64 v[2:3], v[136:137], 0, s[54:55]
	s_add_i32 m0, s63, 0xc000
	ds_read_b128 v[206:209], v179
	ds_read_b128 v[214:217], v179 offset:1024
	ds_read_b128 v[218:221], v179 offset:2048
	ds_read_b128 v[222:225], v179 offset:3072
	ds_read_b128 v[226:229], v179 offset:4096
	ds_read_b128 v[230:233], v179 offset:5120
	ds_read_b128 v[234:237], v179 offset:6144
	ds_read_b128 v[238:241], v179 offset:7168
	global_load_lds_dwordx4 v[2:3], off
	v_lshl_add_u64 v[2:3], v[138:139], 0, s[54:55]
	s_add_i32 m0, s63, 0xe000
	s_nop 0
	global_load_lds_dwordx4 v[2:3], off
	s_waitcnt vmcnt(8)
	s_waitcnt lgkmcnt(0)
	s_barrier
	s_setprio 1
	s_waitcnt lgkmcnt(0)
	v_mfma_f32_16x16x32_bf16 v[128:131], v[140:143], v[206:209], v[128:131]
	v_mfma_f32_16x16x32_bf16 v[128:131], v[144:147], v[214:217], v[128:131]
	v_mfma_f32_16x16x32_bf16 v[124:127], v[148:151], v[206:209], v[124:127]
	v_mfma_f32_16x16x32_bf16 v[124:127], v[152:155], v[214:217], v[124:127]
	v_mfma_f32_16x16x32_bf16 v[112:115], v[140:143], v[218:221], v[112:115]
	v_mfma_f32_16x16x32_bf16 v[112:115], v[144:147], v[222:225], v[112:115]
	v_mfma_f32_16x16x32_bf16 v[108:111], v[148:151], v[218:221], v[108:111]
	v_mfma_f32_16x16x32_bf16 v[108:111], v[152:155], v[222:225], v[108:111]
	v_mfma_f32_16x16x32_bf16 v[96:99], v[140:143], v[226:229], v[96:99]
	v_mfma_f32_16x16x32_bf16 v[96:99], v[144:147], v[230:233], v[96:99]
	v_mfma_f32_16x16x32_bf16 v[92:95], v[148:151], v[226:229], v[92:95]
	v_mfma_f32_16x16x32_bf16 v[92:95], v[152:155], v[230:233], v[92:95]
	v_mfma_f32_16x16x32_bf16 v[80:83], v[140:143], v[234:237], v[80:83]
	v_mfma_f32_16x16x32_bf16 v[80:83], v[144:147], v[238:241], v[80:83]
	v_mfma_f32_16x16x32_bf16 v[76:79], v[148:151], v[234:237], v[76:79]
	v_mfma_f32_16x16x32_bf16 v[76:79], v[152:155], v[238:241], v[76:79]
	v_mfma_f32_16x16x32_bf16 v[120:123], v[190:193], v[206:209], v[120:123]
	v_mfma_f32_16x16x32_bf16 v[120:123], v[194:197], v[214:217], v[120:123]
	v_mfma_f32_16x16x32_bf16 v[116:119], v[198:201], v[206:209], v[116:119]
	v_mfma_f32_16x16x32_bf16 v[116:119], v[202:205], v[214:217], v[116:119]
	v_mfma_f32_16x16x32_bf16 v[104:107], v[190:193], v[218:221], v[104:107]
	v_mfma_f32_16x16x32_bf16 v[104:107], v[194:197], v[222:225], v[104:107]
	v_mfma_f32_16x16x32_bf16 v[100:103], v[198:201], v[218:221], v[100:103]
	v_mfma_f32_16x16x32_bf16 v[100:103], v[202:205], v[222:225], v[100:103]
	v_mfma_f32_16x16x32_bf16 v[88:91], v[190:193], v[226:229], v[88:91]
	v_mfma_f32_16x16x32_bf16 v[88:91], v[194:197], v[230:233], v[88:91]
	v_mfma_f32_16x16x32_bf16 v[84:87], v[198:201], v[226:229], v[84:87]
	v_mfma_f32_16x16x32_bf16 v[84:87], v[202:205], v[230:233], v[84:87]
	v_mfma_f32_16x16x32_bf16 v[72:75], v[190:193], v[234:237], v[72:75]
	v_mfma_f32_16x16x32_bf16 v[72:75], v[194:197], v[238:241], v[72:75]
	v_mfma_f32_16x16x32_bf16 v[68:71], v[198:201], v[234:237], v[68:71]
	v_mfma_f32_16x16x32_bf16 v[68:71], v[202:205], v[238:241], v[68:71]
	s_setprio 0
	s_barrier
	s_add_i32 s33, s70, s62
	v_lshl_add_u64 v[210:211], s[56:57], 0, v[158:159]
	s_mov_b32 m0, s33
	ds_read_b128 v[206:209], v179 offset:16384
	ds_read_b128 v[214:217], v179 offset:17408
	ds_read_b128 v[218:221], v179 offset:18432
	ds_read_b128 v[222:225], v179 offset:19456
	ds_read_b128 v[226:229], v179 offset:20480
	ds_read_b128 v[230:233], v179 offset:21504
	ds_read_b128 v[234:237], v179 offset:22528
	ds_read_b128 v[238:241], v179 offset:23552
	global_load_lds_dwordx4 v[210:211], off
	s_add_i32 m0, s33, 0x2000
	s_add_u32 s76, s56, 0x80000
	v_lshl_add_u64 v[242:243], s[56:57], 0, v[162:163]
	s_addc_u32 s77, s57, 0
	s_add_i32 s33, s71, s62
	global_load_lds_dwordx4 v[242:243], off
	v_lshl_add_u64 v[2:3], s[76:77], 0, v[158:159]
	s_mov_b32 m0, s33
	v_lshl_add_u64 v[244:245], s[58:59], 0, v[156:157]
	global_load_lds_dwordx4 v[2:3], off
	v_lshl_add_u64 v[2:3], s[76:77], 0, v[162:163]
	s_add_i32 m0, s33, 0x2000
	v_lshl_add_u64 v[246:247], s[58:59], 0, v[160:161]
	global_load_lds_dwordx4 v[2:3], off
	s_mov_b32 m0, s63
	s_nop 0
	global_load_lds_dwordx4 v[244:245], off
	s_mov_b32 m0, s64
	s_nop 0
	global_load_lds_dwordx4 v[246:247], off
	s_waitcnt vmcnt(8)
	s_waitcnt lgkmcnt(0)
	s_barrier
; #define PG8_STAGE(bufoff, gbase, voff) do { _Pragma("unroll") for (int _i = 0; _i < 2; ++_i) \
;         __builtin_amdgcn_global_load_lds((const unsigned*)((const char*)(gbase) + (voff)[_i]), (PG8_LAS unsigned*)(lds + (bufoff) + ldsw + _i * 8192), 16, 0, 0); } while (0)
; #define PG8_WAIT_V(n) asm volatile("s_waitcnt vmcnt(" #n ")" ::: "memory")
; #define PG8_WAIT_L(n) asm volatile("s_waitcnt lgkmcnt(" #n ")" ::: "memory")
; #define PG8_BAR __builtin_amdgcn_s_barrier()
; #define PG8_SCHED __builtin_amdgcn_sched_barrier(0)
;     ...
;             PG8_WAIT_V(8); PG8_WAIT_L(0); PG8_BAR; PG8_MMA(1, 0, At, B0); PG8_MMA(1, 1, At, B1); PG8_BAR; PG8_SCHED;
;             PG8_LDB(B0, 1, 0); PG8_LDB(B1, 1, 1); PG8_SCHED; PG8_LDA(At, 1, 0); PG8_STAGE(PG8_SA(0, 1), a2 + hstep, voffA);
;             PG8_WAIT_V(8); PG8_WAIT_L(0); PG8_BAR; PG8_MMA(0, 0, At, B0); PG8_MMA(0, 1, At, B1); PG8_BAR; PG8_SCHED;
	s_setprio 1
	s_waitcnt lgkmcnt(0)
	v_mfma_f32_16x16x32_bf16 v[64:67], v[140:143], v[206:209], v[64:67]
	v_mfma_f32_16x16x32_bf16 v[64:67], v[144:147], v[214:217], v[64:67]
	v_mfma_f32_16x16x32_bf16 v[60:63], v[148:151], v[206:209], v[60:63]
	v_mfma_f32_16x16x32_bf16 v[60:63], v[152:155], v[214:217], v[60:63]
	v_mfma_f32_16x16x32_bf16 v[48:51], v[140:143], v[218:221], v[48:51]
	v_mfma_f32_16x16x32_bf16 v[48:51], v[144:147], v[222:225], v[48:51]
	v_mfma_f32_16x16x32_bf16 v[44:47], v[148:151], v[218:221], v[44:47]
	v_mfma_f32_16x16x32_bf16 v[44:47], v[152:155], v[222:225], v[44:47]
	v_mfma_f32_16x16x32_bf16 v[32:35], v[140:143], v[226:229], v[32:35]
	v_mfma_f32_16x16x32_bf16 v[32:35], v[144:147], v[230:233], v[32:35]
	v_mfma_f32_16x16x32_bf16 v[28:31], v[148:151], v[226:229], v[28:31]
	v_mfma_f32_16x16x32_bf16 v[28:31], v[152:155], v[230:233], v[28:31]
	v_mfma_f32_16x16x32_bf16 v[16:19], v[140:143], v[234:237], v[16:19]
	v_mfma_f32_16x16x32_bf16 v[16:19], v[144:147], v[238:241], v[16:19]
	v_mfma_f32_16x16x32_bf16 v[12:15], v[148:151], v[234:237], v[12:15]
	v_mfma_f32_16x16x32_bf16 v[12:15], v[152:155], v[238:241], v[12:15]
	v_mfma_f32_16x16x32_bf16 v[56:59], v[190:193], v[206:209], v[56:59]
	v_mfma_f32_16x16x32_bf16 v[56:59], v[194:197], v[214:217], v[56:59]
	v_mfma_f32_16x16x32_bf16 v[52:55], v[198:201], v[206:209], v[52:55]
	v_mfma_f32_16x16x32_bf16 v[52:55], v[202:205], v[214:217], v[52:55]
	v_mfma_f32_16x16x32_bf16 v[40:43], v[190:193], v[218:221], v[40:43]
	v_mfma_f32_16x16x32_bf16 v[40:43], v[194:197], v[222:225], v[40:43]
	v_mfma_f32_16x16x32_bf16 v[36:39], v[198:201], v[218:221], v[36:39]
	v_mfma_f32_16x16x32_bf16 v[36:39], v[202:205], v[222:225], v[36:39]
	v_mfma_f32_16x16x32_bf16 v[24:27], v[190:193], v[226:229], v[24:27]
	v_mfma_f32_16x16x32_bf16 v[24:27], v[194:197], v[230:233], v[24:27]
	v_mfma_f32_16x16x32_bf16 v[20:23], v[198:201], v[226:229], v[20:23]
	v_mfma_f32_16x16x32_bf16 v[20:23], v[202:205], v[230:233], v[20:23]
	v_mfma_f32_16x16x32_bf16 v[8:11], v[190:193], v[234:237], v[8:11]
	v_mfma_f32_16x16x32_bf16 v[8:11], v[194:197], v[238:241], v[8:11]
	v_mfma_f32_16x16x32_bf16 v[2:5], v[198:201], v[234:237], v[4:7]
	v_mfma_f32_16x16x32_bf16 v[2:5], v[202:205], v[238:241], v[2:5]
	s_setprio 0
	s_barrier
	s_add_i32 s33, 0, 0x18000
	v_add_u32_e32 v1, s33, v175
	s_add_i32 s76, 0, 0x1c000
	ds_read_b128 v[140:143], v1
	ds_read_b128 v[144:147], v1 offset:1024
	ds_read_b128 v[148:151], v1 offset:2048
	ds_read_b128 v[152:155], v1 offset:3072
	v_add_u32_e32 v1, s76, v175
	ds_read_b128 v[190:193], v1
	ds_read_b128 v[194:197], v1 offset:1024
	ds_read_b128 v[198:201], v1 offset:2048
	ds_read_b128 v[202:205], v1 offset:3072
	s_add_u32 s58, s58, 0x80000
	s_addc_u32 s59, s59, 0
	s_mov_b32 m0, s65
	v_lshl_add_u64 v[6:7], s[58:59], 0, v[156:157]
	ds_read_b128 v[206:209], v179 offset:32768
	ds_read_b128 v[214:217], v179 offset:33792
	ds_read_b128 v[218:221], v179 offset:34816
	ds_read_b128 v[222:225], v179 offset:35840
	ds_read_b128 v[226:229], v179 offset:36864
	ds_read_b128 v[230:233], v179 offset:37888
	ds_read_b128 v[234:237], v179 offset:38912
	ds_read_b128 v[238:241], v179 offset:39936
	global_load_lds_dwordx4 v[6:7], off
	v_lshl_add_u64 v[6:7], s[58:59], 0, v[160:161]
	s_mov_b32 m0, s66
	s_nop 0
	global_load_lds_dwordx4 v[6:7], off
	s_waitcnt vmcnt(8)
	s_waitcnt lgkmcnt(0)
	s_barrier
	s_setprio 1
	s_waitcnt lgkmcnt(0)
	v_mfma_f32_16x16x32_bf16 v[128:131], v[140:143], v[206:209], v[128:131]
	v_mfma_f32_16x16x32_bf16 v[128:131], v[144:147], v[214:217], v[128:131]
	v_mfma_f32_16x16x32_bf16 v[124:127], v[148:151], v[206:209], v[124:127]
	v_mfma_f32_16x16x32_bf16 v[124:127], v[152:155], v[214:217], v[124:127]
	v_mfma_f32_16x16x32_bf16 v[112:115], v[140:143], v[218:221], v[112:115]
	v_mfma_f32_16x16x32_bf16 v[112:115], v[144:147], v[222:225], v[112:115]
	v_mfma_f32_16x16x32_bf16 v[108:111], v[148:151], v[218:221], v[108:111]
	v_mfma_f32_16x16x32_bf16 v[108:111], v[152:155], v[222:225], v[108:111]
	v_mfma_f32_16x16x32_bf16 v[96:99], v[140:143], v[226:229], v[96:99]
	v_mfma_f32_16x16x32_bf16 v[96:99], v[144:147], v[230:233], v[96:99]
	v_mfma_f32_16x16x32_bf16 v[92:95], v[148:151], v[226:229], v[92:95]
	v_mfma_f32_16x16x32_bf16 v[92:95], v[152:155], v[230:233], v[92:95]
	v_mfma_f32_16x16x32_bf16 v[80:83], v[140:143], v[234:237], v[80:83]
	v_mfma_f32_16x16x32_bf16 v[80:83], v[144:147], v[238:241], v[80:83]
	v_mfma_f32_16x16x32_bf16 v[76:79], v[148:151], v[234:237], v[76:79]
	v_mfma_f32_16x16x32_bf16 v[76:79], v[152:155], v[238:241], v[76:79]
	v_mfma_f32_16x16x32_bf16 v[120:123], v[190:193], v[206:209], v[120:123]
	v_mfma_f32_16x16x32_bf16 v[120:123], v[194:197], v[214:217], v[120:123]
	v_mfma_f32_16x16x32_bf16 v[116:119], v[198:201], v[206:209], v[116:119]
	v_mfma_f32_16x16x32_bf16 v[116:119], v[202:205], v[214:217], v[116:119]
	v_mfma_f32_16x16x32_bf16 v[104:107], v[190:193], v[218:221], v[104:107]
	v_mfma_f32_16x16x32_bf16 v[104:107], v[194:197], v[222:225], v[104:107]
	v_mfma_f32_16x16x32_bf16 v[100:103], v[198:201], v[218:221], v[100:103]
	v_mfma_f32_16x16x32_bf16 v[100:103], v[202:205], v[222:225], v[100:103]
	v_mfma_f32_16x16x32_bf16 v[88:91], v[190:193], v[226:229], v[88:91]
	v_mfma_f32_16x16x32_bf16 v[88:91], v[194:197], v[230:233], v[88:91]
	v_mfma_f32_16x16x32_bf16 v[84:87], v[198:201], v[226:229], v[84:87]
	v_mfma_f32_16x16x32_bf16 v[84:87], v[202:205], v[230:233], v[84:87]
	v_mfma_f32_16x16x32_bf16 v[72:75], v[190:193], v[234:237], v[72:75]
	v_mfma_f32_16x16x32_bf16 v[72:75], v[194:197], v[238:241], v[72:75]
	v_mfma_f32_16x16x32_bf16 v[68:71], v[198:201], v[234:237], v[68:71]
	v_mfma_f32_16x16x32_bf16 v[68:71], v[202:205], v[238:241], v[68:71]
	s_setprio 0
	s_barrier
; #define PG8_STAGE(bufoff, gbase, voff) do { _Pragma("unroll") for (int _i = 0; _i < 2; ++_i) \
;         __builtin_amdgcn_global_load_lds((const unsigned*)((const char*)(gbase) + (voff)[_i]), (PG8_LAS unsigned*)(lds + (bufoff) + ldsw + _i * 8192), 16, 0, 0); } while (0)
; #define PG8_WAIT_V(n) asm volatile("s_waitcnt vmcnt(" #n ")" ::: "memory")
; #define PG8_WAIT_L(n) asm volatile("s_waitcnt lgkmcnt(" #n ")" ::: "memory")
; #define PG8_BAR __builtin_amdgcn_s_barrier()
; #define PG8_SCHED __builtin_amdgcn_sched_barrier(0)
;     ...
;             PG8_LDA(At, 1, 1); PG8_STAGE(PG8_SB(1, 0), b3, voffB); PG8_STAGE(PG8_SB(1, 1), b3 + hstep, voffB); PG8_STAGE(PG8_SA(1, 0), a3, voffA);
;             PG8_WAIT_V(8); PG8_WAIT_L(0); PG8_BAR; PG8_MMA(1, 0, At, B0); PG8_MMA(1, 1, At, B1); PG8_BAR; PG8_SCHED;
	s_add_i32 s33, s33, s62
	v_lshl_add_u64 v[6:7], v[210:211], 0, s[40:41]
	s_mov_b32 m0, s33
	ds_read_b128 v[206:209], v179 offset:49152
	ds_read_b128 v[214:217], v179 offset:50176
	ds_read_b128 v[218:221], v179 offset:51200
	ds_read_b128 v[222:225], v179 offset:52224
	ds_read_b128 v[226:229], v179 offset:53248
	ds_read_b128 v[230:233], v179 offset:54272
	ds_read_b128 v[234:237], v179 offset:55296
	ds_read_b128 v[238:241], v179 offset:56320
	global_load_lds_dwordx4 v[6:7], off
	s_add_i32 m0, s33, 0x2000
	s_add_u32 s56, s56, 0x80080
	v_lshl_add_u64 v[6:7], v[242:243], 0, s[40:41]
	s_addc_u32 s57, s57, 0
	s_add_i32 s33, s76, s62
	global_load_lds_dwordx4 v[6:7], off
	v_lshl_add_u64 v[6:7], s[56:57], 0, v[158:159]
	s_mov_b32 m0, s33
	s_nop 0
	global_load_lds_dwordx4 v[6:7], off
	v_lshl_add_u64 v[6:7], s[56:57], 0, v[162:163]
	s_add_i32 m0, s33, 0x2000
	s_nop 0
	global_load_lds_dwordx4 v[6:7], off
	v_lshl_add_u64 v[6:7], v[244:245], 0, s[40:41]
	s_mov_b32 m0, s68
	s_nop 0
	global_load_lds_dwordx4 v[6:7], off
	v_lshl_add_u64 v[6:7], v[246:247], 0, s[40:41]
	s_mov_b32 m0, s69
	s_nop 0
	global_load_lds_dwordx4 v[6:7], off
	s_waitcnt vmcnt(8)
	s_waitcnt lgkmcnt(0)
	s_barrier
	s_setprio 1
	s_waitcnt lgkmcnt(0)
	v_mfma_f32_16x16x32_bf16 v[64:67], v[140:143], v[206:209], v[64:67]
	v_mfma_f32_16x16x32_bf16 v[64:67], v[144:147], v[214:217], v[64:67]
	v_mfma_f32_16x16x32_bf16 v[60:63], v[148:151], v[206:209], v[60:63]
	v_mfma_f32_16x16x32_bf16 v[60:63], v[152:155], v[214:217], v[60:63]
	v_mfma_f32_16x16x32_bf16 v[48:51], v[140:143], v[218:221], v[48:51]
	v_mfma_f32_16x16x32_bf16 v[48:51], v[144:147], v[222:225], v[48:51]
	v_mfma_f32_16x16x32_bf16 v[44:47], v[148:151], v[218:221], v[44:47]
	v_mfma_f32_16x16x32_bf16 v[44:47], v[152:155], v[222:225], v[44:47]
	v_mfma_f32_16x16x32_bf16 v[32:35], v[140:143], v[226:229], v[32:35]
	v_mfma_f32_16x16x32_bf16 v[32:35], v[144:147], v[230:233], v[32:35]
	v_mfma_f32_16x16x32_bf16 v[28:31], v[148:151], v[226:229], v[28:31]
	v_mfma_f32_16x16x32_bf16 v[28:31], v[152:155], v[230:233], v[28:31]
	v_mfma_f32_16x16x32_bf16 v[16:19], v[140:143], v[234:237], v[16:19]
	v_mfma_f32_16x16x32_bf16 v[16:19], v[144:147], v[238:241], v[16:19]
	v_mfma_f32_16x16x32_bf16 v[12:15], v[148:151], v[234:237], v[12:15]
	v_mfma_f32_16x16x32_bf16 v[12:15], v[152:155], v[238:241], v[12:15]
	v_mfma_f32_16x16x32_bf16 v[56:59], v[190:193], v[206:209], v[56:59]
	v_mfma_f32_16x16x32_bf16 v[52:55], v[198:201], v[206:209], v[52:55]
	v_mfma_f32_16x16x32_bf16 v[40:43], v[190:193], v[218:221], v[40:43]
	v_mfma_f32_16x16x32_bf16 v[36:39], v[198:201], v[218:221], v[36:39]
	v_mfma_f32_16x16x32_bf16 v[24:27], v[190:193], v[226:229], v[24:27]
	v_mfma_f32_16x16x32_bf16 v[20:23], v[198:201], v[226:229], v[20:23]
	v_mfma_f32_16x16x32_bf16 v[6:9], v[190:193], v[234:237], v[8:11]
	v_mfma_f32_16x16x32_bf16 v[2:5], v[198:201], v[234:237], v[2:5]
	v_mfma_f32_16x16x32_bf16 v[56:59], v[194:197], v[214:217], v[56:59]
	v_mfma_f32_16x16x32_bf16 v[52:55], v[202:205], v[214:217], v[52:55]
	v_mfma_f32_16x16x32_bf16 v[40:43], v[194:197], v[222:225], v[40:43]
	v_mfma_f32_16x16x32_bf16 v[36:39], v[202:205], v[222:225], v[36:39]
	v_mfma_f32_16x16x32_bf16 v[24:27], v[194:197], v[230:233], v[24:27]
	v_mfma_f32_16x16x32_bf16 v[20:23], v[202:205], v[230:233], v[20:23]
	v_mfma_f32_16x16x32_bf16 v[8:11], v[194:197], v[238:241], v[6:9]
	v_mfma_f32_16x16x32_bf16 v[4:7], v[202:205], v[238:241], v[2:5]
	s_setprio 0
	s_barrier
	s_add_i32 s75, s75, 2
	s_add_u32 s54, s54, 0x100
	s_addc_u32 s55, s55, 0
	s_cmp_gt_u32 s75, 29
	s_cbranch_scc1 .LBB0_671

; #define PG8_STAGE(bufoff, gbase, voff) do { _Pragma("unroll") for (int _i = 0; _i < 2; ++_i) \
;         __builtin_amdgcn_global_load_lds((const unsigned*)((const char*)(gbase) + (voff)[_i]), (PG8_LAS unsigned*)(lds + (bufoff) + ldsw + _i * 8192), 16, 0, 0); } while (0)
; #define PG8_WAIT_V(n) asm volatile("s_waitcnt vmcnt(" #n ")" ::: "memory")
; #define PG8_WAIT_L(n) asm volatile("s_waitcnt lgkmcnt(" #n ")" ::: "memory")
; #define PG8_BAR __builtin_amdgcn_s_barrier()
; #define PG8_SCHED __builtin_amdgcn_sched_barrier(0)
;     ...
;             const char* a1 = cA + (size_t)(t + 1) * kstep;
;             const char* a2 = last ? nA : cA + (size_t)(t + 2) * kstep; const char* b2 = last ? nB : cB + (size_t)(t + 2) * kstep;
;             const char* a3 = a2 + kstep; const char* b3 = b2 + kstep;
;             if (last && has_next) S.a_ready(nxt);
;             if (last) E.pre(pre, cur, wr, fr);
;             if constexpr (MIDK > 0) { if (t == MIDK / BK) E.mid(acc, cur, wr, wc, fr, fq); }
;             if constexpr (SP2) {
;             PG8_LDB(B0, 0, 0); PG8_LDB(B1, 0, 1); PG8_SCHED; PG8_LDA(At, 0, 0); PG8_STAGE(PG8_SA(1, 1), a1 + hstep, voffA);
;             PG8_WAIT_V(8); PG8_WAIT_L(0); PG8_BAR; PG8_MMA(0, 0, At, B0); PG8_MMA(0, 1, At, B1); PG8_BAR; PG8_SCHED;
;             PG8_LDA(At, 0, 1); PG8_STAGE(PG8_SB(0, 0), b2, voffB); PG8_STAGE(PG8_SB(0, 1), b2 + hstep, voffB); PG8_STAGE(PG8_SA(0, 0), a2, voffA);
;             PG8_WAIT_V(8); PG8_WAIT_L(0); PG8_BAR; PG8_MMA(1, 0, At, B0); PG8_MMA(1, 1, At, B1); PG8_BAR; PG8_SCHED;
.LBB0_851:
	v_add_u32_e32 v157, s60, v149
	ds_read_b128 v[166:169], v157
	ds_read_b128 v[170:173], v157 offset:1024
	ds_read_b128 v[174:177], v157 offset:2048
	ds_read_b128 v[178:181], v157 offset:3072
	v_add_u32_e32 v157, s61, v149
	ds_read_b128 v[182:185], v157
	ds_read_b128 v[186:189], v157 offset:1024
	ds_read_b128 v[190:193], v157 offset:2048
	ds_read_b128 v[194:197], v157 offset:3072
	s_add_u32 s33, s42, 0xfffc0080
	s_addc_u32 s46, s43, -1
	s_and_b64 s[44:45], s[44:45], exec
	s_cselect_b32 s47, s34, s46
	s_cselect_b32 s46, s35, s33
	s_cselect_b32 s45, s25, s66
	s_cselect_b32 s44, s37, s65
	v_lshl_add_u64 v[210:211], s[42:43], 0, v[138:139]
	s_add_i32 m0, s51, 0xc000
	ds_read_b128 v[198:201], v153
	ds_read_b128 v[202:205], v153 offset:1024
	ds_read_b128 v[206:209], v153 offset:2048
	ds_read_b128 v[214:217], v153 offset:3072
	ds_read_b128 v[218:221], v153 offset:4096
	ds_read_b128 v[222:225], v153 offset:5120
	ds_read_b128 v[226:229], v153 offset:6144
	ds_read_b128 v[230:233], v153 offset:7168
	global_load_lds_dwordx4 v[210:211], off
	v_lshl_add_u64 v[210:211], s[42:43], 0, v[140:141]
	s_add_i32 m0, s51, 0xe000
	s_nop 0
	global_load_lds_dwordx4 v[210:211], off
	s_waitcnt vmcnt(8)
	s_waitcnt lgkmcnt(0)
	s_barrier
	s_setprio 1
	s_waitcnt lgkmcnt(0)
	v_mfma_i32_16x16x64_i8 v[124:127], v[166:169], v[198:201], v[124:127]
	v_mfma_i32_16x16x64_i8 v[124:127], v[170:173], v[202:205], v[124:127]
	v_mfma_i32_16x16x64_i8 v[120:123], v[174:177], v[198:201], v[120:123]
	v_mfma_i32_16x16x64_i8 v[120:123], v[178:181], v[202:205], v[120:123]
	v_mfma_i32_16x16x64_i8 v[108:111], v[166:169], v[206:209], v[108:111]
	v_mfma_i32_16x16x64_i8 v[108:111], v[170:173], v[214:217], v[108:111]
	v_mfma_i32_16x16x64_i8 v[100:103], v[174:177], v[206:209], v[100:103]
	v_mfma_i32_16x16x64_i8 v[100:103], v[178:181], v[214:217], v[100:103]
	v_mfma_i32_16x16x64_i8 v[92:95], v[166:169], v[218:221], v[92:95]
	v_mfma_i32_16x16x64_i8 v[92:95], v[170:173], v[222:225], v[92:95]
	v_mfma_i32_16x16x64_i8 v[84:87], v[174:177], v[218:221], v[84:87]
	v_mfma_i32_16x16x64_i8 v[84:87], v[178:181], v[222:225], v[84:87]
	v_mfma_i32_16x16x64_i8 v[76:79], v[166:169], v[226:229], v[76:79]
	v_mfma_i32_16x16x64_i8 v[76:79], v[170:173], v[230:233], v[76:79]
	v_mfma_i32_16x16x64_i8 v[68:71], v[174:177], v[226:229], v[68:71]
	v_mfma_i32_16x16x64_i8 v[68:71], v[178:181], v[230:233], v[68:71]
	v_mfma_i32_16x16x64_i8 v[116:119], v[182:185], v[198:201], v[116:119]
	v_mfma_i32_16x16x64_i8 v[116:119], v[186:189], v[202:205], v[116:119]
	v_mfma_i32_16x16x64_i8 v[112:115], v[190:193], v[198:201], v[112:115]
	v_mfma_i32_16x16x64_i8 v[112:115], v[194:197], v[202:205], v[112:115]
	v_mfma_i32_16x16x64_i8 v[104:107], v[182:185], v[206:209], v[104:107]
	v_mfma_i32_16x16x64_i8 v[104:107], v[186:189], v[214:217], v[104:107]
	v_mfma_i32_16x16x64_i8 v[96:99], v[190:193], v[206:209], v[96:99]
	v_mfma_i32_16x16x64_i8 v[96:99], v[194:197], v[214:217], v[96:99]
	v_mfma_i32_16x16x64_i8 v[88:91], v[182:185], v[218:221], v[88:91]
	v_mfma_i32_16x16x64_i8 v[88:91], v[186:189], v[222:225], v[88:91]
	v_mfma_i32_16x16x64_i8 v[80:83], v[190:193], v[218:221], v[80:83]
	v_mfma_i32_16x16x64_i8 v[80:83], v[194:197], v[222:225], v[80:83]
	v_mfma_i32_16x16x64_i8 v[72:75], v[182:185], v[226:229], v[72:75]
	v_mfma_i32_16x16x64_i8 v[72:75], v[186:189], v[230:233], v[72:75]
	v_mfma_i32_16x16x64_i8 v[64:67], v[190:193], v[226:229], v[64:67]
	v_mfma_i32_16x16x64_i8 v[64:67], v[194:197], v[230:233], v[64:67]
	s_setprio 0
	s_barrier
	s_add_i32 s33, s60, s48
	v_lshl_add_u64 v[210:211], s[44:45], 0, v[132:133]
	s_mov_b32 m0, s33
	ds_read_b128 v[198:201], v153 offset:16384
	ds_read_b128 v[202:205], v153 offset:17408
	ds_read_b128 v[206:209], v153 offset:18432
	ds_read_b128 v[214:217], v153 offset:19456
	ds_read_b128 v[218:221], v153 offset:20480
	ds_read_b128 v[222:225], v153 offset:21504
	ds_read_b128 v[226:229], v153 offset:22528
	ds_read_b128 v[230:233], v153 offset:23552
	global_load_lds_dwordx4 v[210:211], off
	s_add_i32 m0, s33, 0x2000
	s_add_u32 s68, s44, 0x40000
	v_lshl_add_u64 v[234:235], s[44:45], 0, v[128:129]
	s_addc_u32 s69, s45, 0
	s_add_i32 s33, s61, s48
	global_load_lds_dwordx4 v[234:235], off
	v_lshl_add_u64 v[236:237], s[68:69], 0, v[132:133]
	s_mov_b32 m0, s33
	v_lshl_add_u64 v[238:239], s[46:47], 0, v[130:131]
	global_load_lds_dwordx4 v[236:237], off
	v_lshl_add_u64 v[236:237], s[68:69], 0, v[128:129]
	s_add_i32 m0, s33, 0x2000
	s_nop 0
	global_load_lds_dwordx4 v[236:237], off
	v_lshl_add_u64 v[236:237], s[46:47], 0, v[134:135]
	s_mov_b32 m0, s51
	s_nop 0
	global_load_lds_dwordx4 v[236:237], off
	s_mov_b32 m0, s52
	s_nop 0
	global_load_lds_dwordx4 v[238:239], off
	s_waitcnt vmcnt(8)
	s_waitcnt lgkmcnt(0)
	s_barrier
; #define PG8_STAGE(bufoff, gbase, voff) do { _Pragma("unroll") for (int _i = 0; _i < 2; ++_i) \
;         __builtin_amdgcn_global_load_lds((const unsigned*)((const char*)(gbase) + (voff)[_i]), (PG8_LAS unsigned*)(lds + (bufoff) + ldsw + _i * 8192), 16, 0, 0); } while (0)
; #define PG8_WAIT_V(n) asm volatile("s_waitcnt vmcnt(" #n ")" ::: "memory")
; #define PG8_WAIT_L(n) asm volatile("s_waitcnt lgkmcnt(" #n ")" ::: "memory")
; #define PG8_BAR __builtin_amdgcn_s_barrier()
; #define PG8_SCHED __builtin_amdgcn_sched_barrier(0)
;     ...
;             PG8_WAIT_V(8); PG8_WAIT_L(0); PG8_BAR; PG8_MMA(1, 0, At, B0); PG8_MMA(1, 1, At, B1); PG8_BAR; PG8_SCHED;
;             PG8_LDB(B0, 1, 0); PG8_LDB(B1, 1, 1); PG8_SCHED; PG8_LDA(At, 1, 0); PG8_STAGE(PG8_SA(0, 1), a2 + hstep, voffA);
;             PG8_WAIT_V(8); PG8_WAIT_L(0); PG8_BAR; PG8_MMA(0, 0, At, B0); PG8_MMA(0, 1, At, B1); PG8_BAR; PG8_SCHED;
	s_setprio 1
	s_waitcnt lgkmcnt(0)
	v_mfma_i32_16x16x64_i8 v[60:63], v[166:169], v[198:201], v[60:63]
	v_mfma_i32_16x16x64_i8 v[60:63], v[170:173], v[202:205], v[60:63]
	v_mfma_i32_16x16x64_i8 v[52:55], v[174:177], v[198:201], v[52:55]
	v_mfma_i32_16x16x64_i8 v[52:55], v[178:181], v[202:205], v[52:55]
	v_mfma_i32_16x16x64_i8 v[44:47], v[166:169], v[206:209], v[44:47]
	v_mfma_i32_16x16x64_i8 v[44:47], v[170:173], v[214:217], v[44:47]
	v_mfma_i32_16x16x64_i8 v[36:39], v[174:177], v[206:209], v[36:39]
	v_mfma_i32_16x16x64_i8 v[36:39], v[178:181], v[214:217], v[36:39]
	v_mfma_i32_16x16x64_i8 v[28:31], v[166:169], v[218:221], v[28:31]
	v_mfma_i32_16x16x64_i8 v[28:31], v[170:173], v[222:225], v[28:31]
	v_mfma_i32_16x16x64_i8 v[20:23], v[174:177], v[218:221], v[20:23]
	v_mfma_i32_16x16x64_i8 v[20:23], v[178:181], v[222:225], v[20:23]
	v_mfma_i32_16x16x64_i8 v[12:15], v[166:169], v[226:229], v[12:15]
	v_mfma_i32_16x16x64_i8 v[12:15], v[170:173], v[230:233], v[12:15]
	v_mfma_i32_16x16x64_i8 v[4:7], v[174:177], v[226:229], v[4:7]
	v_mfma_i32_16x16x64_i8 v[4:7], v[178:181], v[230:233], v[4:7]
	v_mfma_i32_16x16x64_i8 v[56:59], v[182:185], v[198:201], v[56:59]
	v_mfma_i32_16x16x64_i8 v[56:59], v[186:189], v[202:205], v[56:59]
	v_mfma_i32_16x16x64_i8 v[48:51], v[190:193], v[198:201], v[48:51]
	v_mfma_i32_16x16x64_i8 v[48:51], v[194:197], v[202:205], v[48:51]
	v_mfma_i32_16x16x64_i8 v[40:43], v[182:185], v[206:209], v[40:43]
	v_mfma_i32_16x16x64_i8 v[40:43], v[186:189], v[214:217], v[40:43]
	v_mfma_i32_16x16x64_i8 v[32:35], v[190:193], v[206:209], v[32:35]
	v_mfma_i32_16x16x64_i8 v[32:35], v[194:197], v[214:217], v[32:35]
	v_mfma_i32_16x16x64_i8 v[24:27], v[182:185], v[218:221], v[24:27]
	v_mfma_i32_16x16x64_i8 v[24:27], v[186:189], v[222:225], v[24:27]
	v_mfma_i32_16x16x64_i8 v[16:19], v[190:193], v[218:221], v[16:19]
	v_mfma_i32_16x16x64_i8 v[16:19], v[194:197], v[222:225], v[16:19]
	v_mfma_i32_16x16x64_i8 v[8:11], v[182:185], v[226:229], v[8:11]
	v_mfma_i32_16x16x64_i8 v[8:11], v[186:189], v[230:233], v[8:11]
	v_mfma_i32_16x16x64_i8 v[0:3], v[190:193], v[226:229], v[0:3]
	v_mfma_i32_16x16x64_i8 v[0:3], v[194:197], v[230:233], v[0:3]
	s_setprio 0
	s_barrier
	s_add_i32 s33, 0, 0x18000
	v_add_u32_e32 v157, s33, v149
	s_add_i32 s68, 0, 0x1c000
	ds_read_b128 v[166:169], v157
	ds_read_b128 v[170:173], v157 offset:1024
	ds_read_b128 v[174:177], v157 offset:2048
	ds_read_b128 v[178:181], v157 offset:3072
	v_add_u32_e32 v157, s68, v149
	ds_read_b128 v[182:185], v157
	ds_read_b128 v[186:189], v157 offset:1024
	ds_read_b128 v[190:193], v157 offset:2048
	ds_read_b128 v[194:197], v157 offset:3072
	s_add_u32 s46, s46, 0x40000
	s_addc_u32 s47, s47, 0
	s_mov_b32 m0, s53
	v_lshl_add_u64 v[240:241], s[46:47], 0, v[134:135]
	ds_read_b128 v[198:201], v153 offset:32768
	ds_read_b128 v[202:205], v153 offset:33792
	ds_read_b128 v[206:209], v153 offset:34816
	ds_read_b128 v[214:217], v153 offset:35840
	ds_read_b128 v[218:221], v153 offset:36864
	ds_read_b128 v[222:225], v153 offset:37888
	ds_read_b128 v[226:229], v153 offset:38912
	ds_read_b128 v[230:233], v153 offset:39936
	global_load_lds_dwordx4 v[240:241], off
	v_lshl_add_u64 v[240:241], s[46:47], 0, v[130:131]
	s_mov_b32 m0, s54
	s_nop 0
	global_load_lds_dwordx4 v[240:241], off
	s_waitcnt vmcnt(8)
	s_waitcnt lgkmcnt(0)
	s_barrier
	s_setprio 1
	s_waitcnt lgkmcnt(0)
	v_mfma_i32_16x16x64_i8 v[124:127], v[166:169], v[198:201], v[124:127]
	v_mfma_i32_16x16x64_i8 v[124:127], v[170:173], v[202:205], v[124:127]
	v_mfma_i32_16x16x64_i8 v[120:123], v[174:177], v[198:201], v[120:123]
	v_mfma_i32_16x16x64_i8 v[120:123], v[178:181], v[202:205], v[120:123]
	v_mfma_i32_16x16x64_i8 v[108:111], v[166:169], v[206:209], v[108:111]
	v_mfma_i32_16x16x64_i8 v[108:111], v[170:173], v[214:217], v[108:111]
	v_mfma_i32_16x16x64_i8 v[100:103], v[174:177], v[206:209], v[100:103]
	v_mfma_i32_16x16x64_i8 v[100:103], v[178:181], v[214:217], v[100:103]
	v_mfma_i32_16x16x64_i8 v[92:95], v[166:169], v[218:221], v[92:95]
	v_mfma_i32_16x16x64_i8 v[92:95], v[170:173], v[222:225], v[92:95]
	v_mfma_i32_16x16x64_i8 v[84:87], v[174:177], v[218:221], v[84:87]
	v_mfma_i32_16x16x64_i8 v[84:87], v[178:181], v[222:225], v[84:87]
	v_mfma_i32_16x16x64_i8 v[76:79], v[166:169], v[226:229], v[76:79]
	v_mfma_i32_16x16x64_i8 v[76:79], v[170:173], v[230:233], v[76:79]
	v_mfma_i32_16x16x64_i8 v[68:71], v[174:177], v[226:229], v[68:71]
	v_mfma_i32_16x16x64_i8 v[68:71], v[178:181], v[230:233], v[68:71]
	v_mfma_i32_16x16x64_i8 v[116:119], v[182:185], v[198:201], v[116:119]
	v_mfma_i32_16x16x64_i8 v[116:119], v[186:189], v[202:205], v[116:119]
	v_mfma_i32_16x16x64_i8 v[112:115], v[190:193], v[198:201], v[112:115]
	v_mfma_i32_16x16x64_i8 v[112:115], v[194:197], v[202:205], v[112:115]
	v_mfma_i32_16x16x64_i8 v[104:107], v[182:185], v[206:209], v[104:107]
	v_mfma_i32_16x16x64_i8 v[104:107], v[186:189], v[214:217], v[104:107]
	v_mfma_i32_16x16x64_i8 v[96:99], v[190:193], v[206:209], v[96:99]
	v_mfma_i32_16x16x64_i8 v[96:99], v[194:197], v[214:217], v[96:99]
	v_mfma_i32_16x16x64_i8 v[88:91], v[182:185], v[218:221], v[88:91]
	v_mfma_i32_16x16x64_i8 v[88:91], v[186:189], v[222:225], v[88:91]
	v_mfma_i32_16x16x64_i8 v[80:83], v[190:193], v[218:221], v[80:83]
	v_mfma_i32_16x16x64_i8 v[80:83], v[194:197], v[222:225], v[80:83]
	v_mfma_i32_16x16x64_i8 v[72:75], v[182:185], v[226:229], v[72:75]
	v_mfma_i32_16x16x64_i8 v[72:75], v[186:189], v[230:233], v[72:75]
	v_mfma_i32_16x16x64_i8 v[64:67], v[190:193], v[226:229], v[64:67]
	v_mfma_i32_16x16x64_i8 v[64:67], v[194:197], v[230:233], v[64:67]
	s_setprio 0
	s_barrier
; #define PG8_STAGE(bufoff, gbase, voff) do { _Pragma("unroll") for (int _i = 0; _i < 2; ++_i) \
;         __builtin_amdgcn_global_load_lds((const unsigned*)((const char*)(gbase) + (voff)[_i]), (PG8_LAS unsigned*)(lds + (bufoff) + ldsw + _i * 8192), 16, 0, 0); } while (0)
; #define PG8_WAIT_V(n) asm volatile("s_waitcnt vmcnt(" #n ")" ::: "memory")
; #define PG8_WAIT_L(n) asm volatile("s_waitcnt lgkmcnt(" #n ")" ::: "memory")
; #define PG8_BAR __builtin_amdgcn_s_barrier()
; #define PG8_SCHED __builtin_amdgcn_sched_barrier(0)
;     ...
;             PG8_LDA(At, 1, 1); PG8_STAGE(PG8_SB(1, 0), b3, voffB); PG8_STAGE(PG8_SB(1, 1), b3 + hstep, voffB); PG8_STAGE(PG8_SA(1, 0), a3, voffA);
;             PG8_WAIT_V(8); PG8_WAIT_L(0); PG8_BAR; PG8_MMA(1, 0, At, B0); PG8_MMA(1, 1, At, B1); PG8_BAR; PG8_SCHED;
	s_add_i32 s33, s33, s48
	v_lshl_add_u64 v[210:211], v[210:211], 0, s[10:11]
	s_mov_b32 m0, s33
	ds_read_b128 v[198:201], v153 offset:49152
	ds_read_b128 v[202:205], v153 offset:50176
	ds_read_b128 v[206:209], v153 offset:51200
	ds_read_b128 v[214:217], v153 offset:52224
	ds_read_b128 v[218:221], v153 offset:53248
	ds_read_b128 v[222:225], v153 offset:54272
	ds_read_b128 v[226:229], v153 offset:55296
	ds_read_b128 v[230:233], v153 offset:56320
	global_load_lds_dwordx4 v[210:211], off
	s_add_i32 m0, s33, 0x2000
	s_add_u32 s44, s44, 0x40080
	v_lshl_add_u64 v[210:211], v[234:235], 0, s[10:11]
	s_addc_u32 s45, s45, 0
	s_add_i32 s33, s68, s48
	global_load_lds_dwordx4 v[210:211], off
	v_lshl_add_u64 v[210:211], s[44:45], 0, v[132:133]
	s_mov_b32 m0, s33
	s_nop 0
	global_load_lds_dwordx4 v[210:211], off
	v_lshl_add_u64 v[210:211], s[44:45], 0, v[128:129]
	s_add_i32 m0, s33, 0x2000
	s_nop 0
	global_load_lds_dwordx4 v[210:211], off
	v_lshl_add_u64 v[210:211], v[236:237], 0, s[10:11]
	s_mov_b32 m0, s56
	s_nop 0
	global_load_lds_dwordx4 v[210:211], off
	v_lshl_add_u64 v[210:211], v[238:239], 0, s[10:11]
	s_mov_b32 m0, s57
	s_nop 0
	global_load_lds_dwordx4 v[210:211], off
	s_waitcnt vmcnt(8)
	s_waitcnt lgkmcnt(0)
	s_barrier
	s_setprio 1
	s_waitcnt lgkmcnt(0)
	v_mfma_i32_16x16x64_i8 v[60:63], v[166:169], v[198:201], v[60:63]
	v_mfma_i32_16x16x64_i8 v[60:63], v[170:173], v[202:205], v[60:63]
	v_mfma_i32_16x16x64_i8 v[52:55], v[174:177], v[198:201], v[52:55]
	v_mfma_i32_16x16x64_i8 v[52:55], v[178:181], v[202:205], v[52:55]
	v_mfma_i32_16x16x64_i8 v[44:47], v[166:169], v[206:209], v[44:47]
	v_mfma_i32_16x16x64_i8 v[44:47], v[170:173], v[214:217], v[44:47]
	v_mfma_i32_16x16x64_i8 v[36:39], v[174:177], v[206:209], v[36:39]
	v_mfma_i32_16x16x64_i8 v[36:39], v[178:181], v[214:217], v[36:39]
	v_mfma_i32_16x16x64_i8 v[28:31], v[166:169], v[218:221], v[28:31]
	v_mfma_i32_16x16x64_i8 v[28:31], v[170:173], v[222:225], v[28:31]
	v_mfma_i32_16x16x64_i8 v[20:23], v[174:177], v[218:221], v[20:23]
	v_mfma_i32_16x16x64_i8 v[20:23], v[178:181], v[222:225], v[20:23]
	v_mfma_i32_16x16x64_i8 v[12:15], v[166:169], v[226:229], v[12:15]
	v_mfma_i32_16x16x64_i8 v[12:15], v[170:173], v[230:233], v[12:15]
	v_mfma_i32_16x16x64_i8 v[4:7], v[174:177], v[226:229], v[4:7]
	v_mfma_i32_16x16x64_i8 v[4:7], v[178:181], v[230:233], v[4:7]
	v_mfma_i32_16x16x64_i8 v[56:59], v[182:185], v[198:201], v[56:59]
	v_mfma_i32_16x16x64_i8 v[56:59], v[186:189], v[202:205], v[56:59]
	v_mfma_i32_16x16x64_i8 v[48:51], v[190:193], v[198:201], v[48:51]
	v_mfma_i32_16x16x64_i8 v[48:51], v[194:197], v[202:205], v[48:51]
	v_mfma_i32_16x16x64_i8 v[40:43], v[182:185], v[206:209], v[40:43]
	v_mfma_i32_16x16x64_i8 v[40:43], v[186:189], v[214:217], v[40:43]
	v_mfma_i32_16x16x64_i8 v[32:35], v[190:193], v[206:209], v[32:35]
	v_mfma_i32_16x16x64_i8 v[32:35], v[194:197], v[214:217], v[32:35]
	v_mfma_i32_16x16x64_i8 v[24:27], v[182:185], v[218:221], v[24:27]
	v_mfma_i32_16x16x64_i8 v[24:27], v[186:189], v[222:225], v[24:27]
	v_mfma_i32_16x16x64_i8 v[16:19], v[190:193], v[218:221], v[16:19]
	v_mfma_i32_16x16x64_i8 v[16:19], v[194:197], v[222:225], v[16:19]
	v_mfma_i32_16x16x64_i8 v[8:11], v[182:185], v[226:229], v[8:11]
	v_mfma_i32_16x16x64_i8 v[8:11], v[186:189], v[230:233], v[8:11]
	v_mfma_i32_16x16x64_i8 v[0:3], v[190:193], v[226:229], v[0:3]
	v_mfma_i32_16x16x64_i8 v[0:3], v[194:197], v[230:233], v[0:3]
	s_setprio 0
	s_barrier
	s_add_i32 s67, s67, 2
	s_add_u32 s42, s42, 0x100
	s_addc_u32 s43, s43, 0
	s_add_u32 s65, s65, 0x100
	s_addc_u32 s66, s66, 0
	s_cmp_gt_u32 s67, 13
	s_cbranch_scc1 .LBB0_854

; #define PG8_STAGE(bufoff, gbase, voff) do { _Pragma("unroll") for (int _i = 0; _i < 2; ++_i) \
;         __builtin_amdgcn_global_load_lds((const unsigned*)((const char*)(gbase) + (voff)[_i]), (PG8_LAS unsigned*)(lds + (bufoff) + ldsw + _i * 8192), 16, 0, 0); } while (0)
; #define PG8_WAIT_V(n) asm volatile("s_waitcnt vmcnt(" #n ")" ::: "memory")
; #define PG8_WAIT_L(n) asm volatile("s_waitcnt lgkmcnt(" #n ")" ::: "memory")
; #define PG8_BAR __builtin_amdgcn_s_barrier()
; #define PG8_SCHED __builtin_amdgcn_sched_barrier(0)
;     ...
;             const char* a1 = cA + (size_t)(t + 1) * kstep;
;             const char* a2 = last ? nA : cA + (size_t)(t + 2) * kstep; const char* b2 = last ? nB : cB + (size_t)(t + 2) * kstep;
;             const char* a3 = a2 + kstep; const char* b3 = b2 + kstep;
;             if (last && has_next) S.a_ready(nxt);
;             if (last) E.pre(pre, cur, wr, fr);
;             if constexpr (MIDK > 0) { if (t == MIDK / BK) E.mid(acc, cur, wr, wc, fr, fq); }
;             if constexpr (SP2) {
;             PG8_LDB(B0, 0, 0); PG8_LDB(B1, 0, 1); PG8_SCHED; PG8_LDA(At, 0, 0); PG8_STAGE(PG8_SA(1, 1), a1 + hstep, voffA);
;             PG8_WAIT_V(8); PG8_WAIT_L(0); PG8_BAR; PG8_MMA(0, 0, At, B0); PG8_MMA(0, 1, At, B1); PG8_BAR; PG8_SCHED;
;             PG8_LDA(At, 0, 1); PG8_STAGE(PG8_SB(0, 0), b2, voffB); PG8_STAGE(PG8_SB(0, 1), b2 + hstep, voffB); PG8_STAGE(PG8_SA(0, 0), a2, voffA);
;             PG8_WAIT_V(8); PG8_WAIT_L(0); PG8_BAR; PG8_MMA(1, 0, At, B0); PG8_MMA(1, 1, At, B1); PG8_BAR; PG8_SCHED;
.LBB0_936:
	ds_read_b128 v[16:19], v187
	ds_read_b128 v[20:23], v187 offset:16
	ds_read_b128 v[24:27], v187 offset:2048
	ds_read_b128 v[28:31], v187 offset:2064
	ds_read_b128 v[0:3], v188
	ds_read_b128 v[4:7], v188 offset:16
	ds_read_b128 v[8:11], v188 offset:2048
	ds_read_b128 v[12:15], v188 offset:2064
	s_add_u32 s24, s20, 0xfff50080
	s_addc_u32 s25, s21, -1
	s_cmp_eq_u32 s48, 40
	s_cselect_b32 s29, s5, s25
	s_cselect_b32 s28, s4, s24
	s_cselect_b32 s25, s19, s47
	s_cselect_b32 s24, s18, s46
	v_lshl_add_u64 v[214:215], s[20:21], 0, v[168:169]
	s_add_i32 m0, s31, 0xc000
	ds_read_b128 v[176:179], v189
	ds_read_b128 v[180:183], v189 offset:16
	ds_read_b128 v[190:193], v189 offset:2048
	ds_read_b128 v[194:197], v189 offset:2064
	ds_read_b128 v[198:201], v189 offset:4096
	ds_read_b128 v[202:205], v189 offset:4112
	ds_read_b128 v[206:209], v189 offset:6144
	ds_read_b128 v[210:213], v189 offset:6160
	global_load_lds_dwordx4 v[214:215], off
	v_lshl_add_u64 v[214:215], s[20:21], 0, v[170:171]
	s_add_i32 m0, s31, 0xe000
	s_nop 0
	global_load_lds_dwordx4 v[214:215], off
	s_waitcnt vmcnt(8)
	s_waitcnt lgkmcnt(0)
	s_barrier
	s_setprio 1
	s_waitcnt lgkmcnt(0)
	v_mfma_f32_16x16x128_f8f6f4 v[156:159], v[16:23], v[176:183], v[156:159]
	v_mfma_f32_16x16x128_f8f6f4 v[152:155], v[24:31], v[176:183], v[152:155]
	v_mfma_f32_16x16x128_f8f6f4 v[148:151], v[16:23], v[190:197], v[148:151]
	v_mfma_f32_16x16x128_f8f6f4 v[144:147], v[24:31], v[190:197], v[144:147]
	v_mfma_f32_16x16x128_f8f6f4 v[128:131], v[16:23], v[198:205], v[128:131]
	v_mfma_f32_16x16x128_f8f6f4 v[120:123], v[24:31], v[198:205], v[120:123]
	v_mfma_f32_16x16x128_f8f6f4 v[112:115], v[16:23], v[206:213], v[112:115]
	v_mfma_f32_16x16x128_f8f6f4 v[104:107], v[24:31], v[206:213], v[104:107]
	v_mfma_f32_16x16x128_f8f6f4 v[140:143], v[0:7], v[176:183], v[140:143]
	v_mfma_f32_16x16x128_f8f6f4 v[136:139], v[8:15], v[176:183], v[136:139]
	v_mfma_f32_16x16x128_f8f6f4 v[132:135], v[0:7], v[190:197], v[132:135]
	v_mfma_f32_16x16x128_f8f6f4 v[124:127], v[8:15], v[190:197], v[124:127]
	v_mfma_f32_16x16x128_f8f6f4 v[116:119], v[0:7], v[198:205], v[116:119]
	v_mfma_f32_16x16x128_f8f6f4 v[108:111], v[8:15], v[198:205], v[108:111]
	v_mfma_f32_16x16x128_f8f6f4 v[100:103], v[0:7], v[206:213], v[100:103]
	v_mfma_f32_16x16x128_f8f6f4 v[96:99], v[8:15], v[206:213], v[96:99]
	s_setprio 0
	s_barrier
	s_add_i32 s49, s40, s30
	v_lshl_add_u64 v[176:177], s[24:25], 0, v[162:163]
	s_mov_b32 m0, s49
	ds_read_b128 v[190:193], v189 offset:16384
	ds_read_b128 v[194:197], v189 offset:16400
	ds_read_b128 v[198:201], v189 offset:18432
	ds_read_b128 v[202:205], v189 offset:18448
	ds_read_b128 v[206:209], v189 offset:20480
	ds_read_b128 v[210:213], v189 offset:20496
	ds_read_b128 v[214:217], v189 offset:22528
	ds_read_b128 v[218:221], v189 offset:22544
	global_load_lds_dwordx4 v[176:177], off
	s_add_i32 m0, s49, 0x2000
	s_add_u32 s50, s24, 0xb0000
	v_lshl_add_u64 v[178:179], s[24:25], 0, v[166:167]
	s_addc_u32 s51, s25, 0
	s_add_i32 s49, s41, s30
	global_load_lds_dwordx4 v[178:179], off
	v_lshl_add_u64 v[180:181], s[50:51], 0, v[162:163]
	s_mov_b32 m0, s49
	v_lshl_add_u64 v[182:183], s[28:29], 0, v[164:165]
	global_load_lds_dwordx4 v[180:181], off
	v_lshl_add_u64 v[180:181], s[50:51], 0, v[166:167]
	s_add_i32 m0, s49, 0x2000
	s_nop 0
	global_load_lds_dwordx4 v[180:181], off
	v_lshl_add_u64 v[180:181], s[28:29], 0, v[160:161]
	s_mov_b32 m0, s31
	s_nop 0
	global_load_lds_dwordx4 v[180:181], off
	s_mov_b32 m0, s33
	s_nop 0
	global_load_lds_dwordx4 v[182:183], off
	s_waitcnt vmcnt(8)
	s_waitcnt lgkmcnt(0)
	s_barrier
	s_setprio 1
	s_waitcnt lgkmcnt(0)
	v_mfma_f32_16x16x128_f8f6f4 v[92:95], v[16:23], v[190:197], v[92:95]
	v_mfma_f32_16x16x128_f8f6f4 v[88:91], v[24:31], v[190:197], v[88:91]
	v_mfma_f32_16x16x128_f8f6f4 v[80:83], v[16:23], v[198:205], v[80:83]
	v_mfma_f32_16x16x128_f8f6f4 v[72:75], v[24:31], v[198:205], v[72:75]
	v_mfma_f32_16x16x128_f8f6f4 v[64:67], v[16:23], v[206:213], v[64:67]
	v_mfma_f32_16x16x128_f8f6f4 v[56:59], v[24:31], v[206:213], v[56:59]
	v_mfma_f32_16x16x128_f8f6f4 v[48:51], v[16:23], v[214:221], v[48:51]
	v_mfma_f32_16x16x128_f8f6f4 v[40:43], v[24:31], v[214:221], v[40:43]
	v_mfma_f32_16x16x128_f8f6f4 v[84:87], v[0:7], v[190:197], v[84:87]
	v_mfma_f32_16x16x128_f8f6f4 v[76:79], v[8:15], v[190:197], v[76:79]
	v_mfma_f32_16x16x128_f8f6f4 v[68:71], v[0:7], v[198:205], v[68:71]
	v_mfma_f32_16x16x128_f8f6f4 v[60:63], v[8:15], v[198:205], v[60:63]
	v_mfma_f32_16x16x128_f8f6f4 v[52:55], v[0:7], v[206:213], v[52:55]
	v_mfma_f32_16x16x128_f8f6f4 v[44:47], v[8:15], v[206:213], v[44:47]
	v_mfma_f32_16x16x128_f8f6f4 v[36:39], v[0:7], v[214:221], v[36:39]
	v_mfma_f32_16x16x128_f8f6f4 v[32:35], v[8:15], v[214:221], v[32:35]
	s_setprio 0
	s_barrier
; #define PG8_STAGE(bufoff, gbase, voff) do { _Pragma("unroll") for (int _i = 0; _i < 2; ++_i) \
;         __builtin_amdgcn_global_load_lds((const unsigned*)((const char*)(gbase) + (voff)[_i]), (PG8_LAS unsigned*)(lds + (bufoff) + ldsw + _i * 8192), 16, 0, 0); } while (0)
; #define PG8_WAIT_V(n) asm volatile("s_waitcnt vmcnt(" #n ")" ::: "memory")
; #define PG8_WAIT_L(n) asm volatile("s_waitcnt lgkmcnt(" #n ")" ::: "memory")
; #define PG8_BAR __builtin_amdgcn_s_barrier()
; #define PG8_SCHED __builtin_amdgcn_sched_barrier(0)
;     ...
;             PG8_LDB(B0, 1, 0); PG8_LDB(B1, 1, 1); PG8_SCHED; PG8_LDA(At, 1, 0); PG8_STAGE(PG8_SA(0, 1), a2 + hstep, voffA);
;             PG8_WAIT_V(8); PG8_WAIT_L(0); PG8_BAR; PG8_MMA(0, 0, At, B0); PG8_MMA(0, 1, At, B1); PG8_BAR; PG8_SCHED;
;             PG8_LDA(At, 1, 1); PG8_STAGE(PG8_SB(1, 0), b3, voffB); PG8_STAGE(PG8_SB(1, 1), b3 + hstep, voffB); PG8_STAGE(PG8_SA(1, 0), a3, voffA);
;             PG8_WAIT_V(8); PG8_WAIT_L(0); PG8_BAR; PG8_MMA(1, 0, At, B0); PG8_MMA(1, 1, At, B1); PG8_BAR; PG8_SCHED;
;     ...
;         if constexpr (F8) asm volatile("s_nop 15\n\ts_nop 15" ::: "memory");
;         if constexpr (ALIGN_EPI) { if (wr == 0) PG8_BAR; }
	s_add_i32 s49, 0, 0x18000
	s_add_i32 s50, 0, 0x1c000
	v_add_u32_e32 v12, s49, v185
	v_add_u32_e32 v28, s50, v185
	ds_read_b128 v[0:3], v12
	ds_read_b128 v[4:7], v12 offset:16
	ds_read_b128 v[8:11], v12 offset:2048
	ds_read_b128 v[12:15], v12 offset:2064
	ds_read_b128 v[16:19], v28
	ds_read_b128 v[20:23], v28 offset:16
	ds_read_b128 v[24:27], v28 offset:2048
	ds_read_b128 v[28:31], v28 offset:2064
	s_add_u32 s28, s28, 0xb0000
	s_addc_u32 s29, s29, 0
	s_mov_b32 m0, s34
	v_lshl_add_u64 v[222:223], s[28:29], 0, v[160:161]
	ds_read_b128 v[190:193], v189 offset:32768
	ds_read_b128 v[194:197], v189 offset:32784
	ds_read_b128 v[198:201], v189 offset:34816
	ds_read_b128 v[202:205], v189 offset:34832
	ds_read_b128 v[206:209], v189 offset:36864
	ds_read_b128 v[210:213], v189 offset:36880
	ds_read_b128 v[214:217], v189 offset:38912
	ds_read_b128 v[218:221], v189 offset:38928
	global_load_lds_dwordx4 v[222:223], off
	v_lshl_add_u64 v[222:223], s[28:29], 0, v[164:165]
	s_mov_b32 m0, s35
	s_nop 0
	global_load_lds_dwordx4 v[222:223], off
	s_waitcnt vmcnt(8)
	s_waitcnt lgkmcnt(0)
	s_barrier
	s_setprio 1
	s_waitcnt lgkmcnt(0)
	v_mfma_f32_16x16x128_f8f6f4 v[156:159], v[0:7], v[190:197], v[156:159]
	v_mfma_f32_16x16x128_f8f6f4 v[152:155], v[8:15], v[190:197], v[152:155]
	v_mfma_f32_16x16x128_f8f6f4 v[148:151], v[0:7], v[198:205], v[148:151]
	v_mfma_f32_16x16x128_f8f6f4 v[144:147], v[8:15], v[198:205], v[144:147]
	v_mfma_f32_16x16x128_f8f6f4 v[128:131], v[0:7], v[206:213], v[128:131]
	v_mfma_f32_16x16x128_f8f6f4 v[120:123], v[8:15], v[206:213], v[120:123]
	v_mfma_f32_16x16x128_f8f6f4 v[112:115], v[0:7], v[214:221], v[112:115]
	v_mfma_f32_16x16x128_f8f6f4 v[104:107], v[8:15], v[214:221], v[104:107]
	v_mfma_f32_16x16x128_f8f6f4 v[140:143], v[16:23], v[190:197], v[140:143]
	v_mfma_f32_16x16x128_f8f6f4 v[136:139], v[24:31], v[190:197], v[136:139]
	v_mfma_f32_16x16x128_f8f6f4 v[132:135], v[16:23], v[198:205], v[132:135]
	v_mfma_f32_16x16x128_f8f6f4 v[124:127], v[24:31], v[198:205], v[124:127]
	v_mfma_f32_16x16x128_f8f6f4 v[116:119], v[16:23], v[206:213], v[116:119]
	v_mfma_f32_16x16x128_f8f6f4 v[108:111], v[24:31], v[206:213], v[108:111]
	v_mfma_f32_16x16x128_f8f6f4 v[100:103], v[16:23], v[214:221], v[100:103]
	v_mfma_f32_16x16x128_f8f6f4 v[96:99], v[24:31], v[214:221], v[96:99]
	s_setprio 0
	s_barrier
	s_add_i32 s28, s49, s30
	v_lshl_add_u64 v[176:177], v[176:177], 0, s[8:9]
	s_mov_b32 m0, s28
	ds_read_b128 v[190:193], v189 offset:49152
	ds_read_b128 v[194:197], v189 offset:49168
	ds_read_b128 v[198:201], v189 offset:51200
	ds_read_b128 v[202:205], v189 offset:51216
	ds_read_b128 v[206:209], v189 offset:53248
	ds_read_b128 v[210:213], v189 offset:53264
	ds_read_b128 v[214:217], v189 offset:55296
	ds_read_b128 v[218:221], v189 offset:55312
	global_load_lds_dwordx4 v[176:177], off
	s_add_i32 m0, s28, 0x2000
	s_add_u32 s24, s24, 0xb0080
	v_lshl_add_u64 v[176:177], v[178:179], 0, s[8:9]
	s_addc_u32 s25, s25, 0
	s_add_i32 s28, s50, s30
	global_load_lds_dwordx4 v[176:177], off
	v_lshl_add_u64 v[176:177], s[24:25], 0, v[162:163]
	s_mov_b32 m0, s28
	s_nop 0
	global_load_lds_dwordx4 v[176:177], off
	v_lshl_add_u64 v[176:177], s[24:25], 0, v[166:167]
	s_add_i32 m0, s28, 0x2000
	s_nop 0
	global_load_lds_dwordx4 v[176:177], off
	v_lshl_add_u64 v[176:177], v[180:181], 0, s[8:9]
	s_mov_b32 m0, s37
	s_nop 0
	global_load_lds_dwordx4 v[176:177], off
	v_lshl_add_u64 v[176:177], v[182:183], 0, s[8:9]
	s_mov_b32 m0, s38
	s_nop 0
	global_load_lds_dwordx4 v[176:177], off
	s_waitcnt vmcnt(8)
	s_waitcnt lgkmcnt(0)
	s_barrier
	s_setprio 1
	s_waitcnt lgkmcnt(0)
	v_mfma_f32_16x16x128_f8f6f4 v[92:95], v[0:7], v[190:197], v[92:95]
	v_mfma_f32_16x16x128_f8f6f4 v[88:91], v[8:15], v[190:197], v[88:91]
	v_mfma_f32_16x16x128_f8f6f4 v[80:83], v[0:7], v[198:205], v[80:83]
	v_mfma_f32_16x16x128_f8f6f4 v[72:75], v[8:15], v[198:205], v[72:75]
	v_mfma_f32_16x16x128_f8f6f4 v[64:67], v[0:7], v[206:213], v[64:67]
	v_mfma_f32_16x16x128_f8f6f4 v[56:59], v[8:15], v[206:213], v[56:59]
	v_mfma_f32_16x16x128_f8f6f4 v[48:51], v[0:7], v[214:221], v[48:51]
	v_mfma_f32_16x16x128_f8f6f4 v[40:43], v[8:15], v[214:221], v[40:43]
	v_mfma_f32_16x16x128_f8f6f4 v[84:87], v[16:23], v[190:197], v[84:87]
	v_mfma_f32_16x16x128_f8f6f4 v[76:79], v[24:31], v[190:197], v[76:79]
	v_mfma_f32_16x16x128_f8f6f4 v[68:71], v[16:23], v[198:205], v[68:71]
	v_mfma_f32_16x16x128_f8f6f4 v[60:63], v[24:31], v[198:205], v[60:63]
	v_mfma_f32_16x16x128_f8f6f4 v[52:55], v[16:23], v[206:213], v[52:55]
	v_mfma_f32_16x16x128_f8f6f4 v[44:47], v[24:31], v[206:213], v[44:47]
	v_mfma_f32_16x16x128_f8f6f4 v[36:39], v[16:23], v[214:221], v[36:39]
	v_mfma_f32_16x16x128_f8f6f4 v[32:35], v[24:31], v[214:221], v[32:35]
	s_setprio 0
	s_barrier
	s_add_i32 s48, s48, 2
	s_add_u32 s20, s20, 0x100
	s_addc_u32 s21, s21, 0
	s_add_u32 s46, s46, 0x100
	s_addc_u32 s47, s47, 0
	s_cmp_gt_u32 s48, 41
	s_cbranch_scc0 .LBB0_936
	s_nop 15
	s_nop 15
	s_and_b64 vcc, exec, s[10:11]
	s_cbranch_vccz .LBB0_939
	s_barrier
